# leading half takes its pre-epilogue alignment barrier after issuing the epilogue's first loads / LDS table reads
# speedup vs baseline: 1.0323x; 1.0015x over previous
.LBB0_133:
	s_add_u32 vcc_lo, s0, 0xffffc000
	s_addc_u32 vcc_hi, s1, -1
	s_mov_b32 m0, s52
	s_nop 0
	global_load_lds_dwordx4 v158, vcc
	s_mov_b32 m0, s53
	s_nop 0
	global_load_lds_dwordx4 v160, vcc
	ds_read_b128 v[130:133], v224
	ds_read_b128 v[134:137], v224 offset:1024
	ds_read_b128 v[138:141], v224 offset:2048
	ds_read_b128 v[142:145], v224 offset:3072
	ds_read_b128 v[146:149], v224 offset:16384
	ds_read_b128 v[162:165], v224 offset:17408
	ds_read_b128 v[166:169], v224 offset:18432
	ds_read_b128 v[170:173], v224 offset:19456
	ds_read_b128 v[174:177], v225
	ds_read_b128 v[178:181], v225 offset:1024
	ds_read_b128 v[182:185], v225 offset:2048
	ds_read_b128 v[186:189], v225 offset:3072
	ds_read_b128 v[190:193], v225 offset:4096
	ds_read_b128 v[204:207], v225 offset:5120
	ds_read_b128 v[208:211], v225 offset:6144
	ds_read_b128 v[212:215], v225 offset:7168
	s_add_u32 s4, s0, 0x100
	s_addc_u32 s5, s1, 0
	s_add_i32 s58, 0, 0x10000
	s_cmp_eq_u32 s57, 28
	s_cselect_b32 s35, s27, s5
	s_cselect_b32 s34, s26, s4
	s_cselect_b32 s31, s25, s51
	s_cselect_b32 s30, s37, s50
	s_add_i32 s59, 0, 0x14000
	s_add_i32 m0, s38, 0xc000
	s_nop 0
	global_load_lds_dwordx4 v158, s[0:1]
	s_add_i32 m0, s38, 0xe000
	s_nop 0
	global_load_lds_dwordx4 v160, s[0:1]
	s_waitcnt vmcnt(8)
	s_waitcnt lgkmcnt(0)
	v_mfma_f32_16x16x32_bf16 v[126:129], v[130:133], v[174:177], v[126:129]
	v_mfma_f32_16x16x32_bf16 v[126:129], v[134:137], v[178:181], v[126:129]
	s_barrier
	s_setprio 1
	v_mfma_f32_16x16x32_bf16 v[122:125], v[142:145], v[178:181], v[122:125]
	v_mfma_f32_16x16x32_bf16 v[122:125], v[138:141], v[174:177], v[122:125]
	v_mfma_f32_16x16x32_bf16 v[106:109], v[138:141], v[182:185], v[106:109]
	v_mfma_f32_16x16x32_bf16 v[106:109], v[142:145], v[186:189], v[106:109]
	v_mfma_f32_16x16x32_bf16 v[110:113], v[134:137], v[186:189], v[110:113]
	v_mfma_f32_16x16x32_bf16 v[110:113], v[130:133], v[182:185], v[110:113]
	v_mfma_f32_16x16x32_bf16 v[94:97], v[130:133], v[190:193], v[94:97]
	v_mfma_f32_16x16x32_bf16 v[94:97], v[134:137], v[204:207], v[94:97]
	v_mfma_f32_16x16x32_bf16 v[90:93], v[142:145], v[204:207], v[90:93]
	v_mfma_f32_16x16x32_bf16 v[90:93], v[138:141], v[190:193], v[90:93]
	v_mfma_f32_16x16x32_bf16 v[74:77], v[138:141], v[208:211], v[74:77]
	v_mfma_f32_16x16x32_bf16 v[74:77], v[142:145], v[212:215], v[74:77]
	v_mfma_f32_16x16x32_bf16 v[78:81], v[134:137], v[212:215], v[78:81]
	v_mfma_f32_16x16x32_bf16 v[78:81], v[130:133], v[208:211], v[78:81]
	v_mfma_f32_16x16x32_bf16 v[118:121], v[146:149], v[174:177], v[118:121]
	v_mfma_f32_16x16x32_bf16 v[118:121], v[162:165], v[178:181], v[118:121]
	v_mfma_f32_16x16x32_bf16 v[114:117], v[170:173], v[178:181], v[114:117]
	v_mfma_f32_16x16x32_bf16 v[114:117], v[166:169], v[174:177], v[114:117]
	v_mfma_f32_16x16x32_bf16 v[98:101], v[166:169], v[182:185], v[98:101]
	v_mfma_f32_16x16x32_bf16 v[98:101], v[170:173], v[186:189], v[98:101]
	v_mfma_f32_16x16x32_bf16 v[102:105], v[162:165], v[186:189], v[102:105]
	v_mfma_f32_16x16x32_bf16 v[102:105], v[146:149], v[182:185], v[102:105]
	v_mfma_f32_16x16x32_bf16 v[86:89], v[146:149], v[190:193], v[86:89]
	v_mfma_f32_16x16x32_bf16 v[86:89], v[162:165], v[204:207], v[86:89]
	v_mfma_f32_16x16x32_bf16 v[82:85], v[170:173], v[204:207], v[82:85]
	v_mfma_f32_16x16x32_bf16 v[82:85], v[166:169], v[190:193], v[82:85]
	v_mfma_f32_16x16x32_bf16 v[66:69], v[166:169], v[208:211], v[66:69]
	v_mfma_f32_16x16x32_bf16 v[66:69], v[170:173], v[212:215], v[66:69]
	v_mfma_f32_16x16x32_bf16 v[70:73], v[162:165], v[212:215], v[70:73]
	v_mfma_f32_16x16x32_bf16 v[70:73], v[146:149], v[208:211], v[70:73]
	s_setprio 0
	s_barrier
	ds_read_b128 v[174:177], v225 offset:16384
	ds_read_b128 v[178:181], v225 offset:17408
	ds_read_b128 v[182:185], v225 offset:18432
	ds_read_b128 v[186:189], v225 offset:19456
	ds_read_b128 v[190:193], v225 offset:20480
	ds_read_b128 v[204:207], v225 offset:21504
	ds_read_b128 v[208:211], v225 offset:22528
	ds_read_b128 v[212:215], v225 offset:23552
	s_add_i32 s0, s58, s15
	s_mov_b32 m0, s0
	s_nop 0
	global_load_lds_dwordx4 v152, s[30:31]
	s_add_i32 m0, s0, 0x2000
	s_add_u32 s0, s30, 0x80000
	s_addc_u32 s1, s31, 0
	s_add_i32 s58, s59, s15
	global_load_lds_dwordx4 v156, s[30:31]
	s_mov_b32 m0, s58
	s_nop 0
	global_load_lds_dwordx4 v152, s[0:1]
	s_add_i32 m0, s58, 0x2000
	s_nop 0
	global_load_lds_dwordx4 v156, s[0:1]
	s_waitcnt vmcnt(6)
	s_waitcnt lgkmcnt(0)
	v_mfma_f32_16x16x32_bf16 v[62:65], v[130:133], v[174:177], v[62:65]
	v_mfma_f32_16x16x32_bf16 v[62:65], v[134:137], v[178:181], v[62:65]
	s_barrier
	s_setprio 1
	v_mfma_f32_16x16x32_bf16 v[58:61], v[142:145], v[178:181], v[58:61]
	v_mfma_f32_16x16x32_bf16 v[58:61], v[138:141], v[174:177], v[58:61]
	v_mfma_f32_16x16x32_bf16 v[42:45], v[138:141], v[182:185], v[42:45]
	v_mfma_f32_16x16x32_bf16 v[42:45], v[142:145], v[186:189], v[42:45]
	v_mfma_f32_16x16x32_bf16 v[46:49], v[134:137], v[186:189], v[46:49]
	v_mfma_f32_16x16x32_bf16 v[46:49], v[130:133], v[182:185], v[46:49]
	v_mfma_f32_16x16x32_bf16 v[30:33], v[130:133], v[190:193], v[30:33]
	v_mfma_f32_16x16x32_bf16 v[30:33], v[134:137], v[204:207], v[30:33]
	v_mfma_f32_16x16x32_bf16 v[26:29], v[142:145], v[204:207], v[26:29]
	v_mfma_f32_16x16x32_bf16 v[26:29], v[138:141], v[190:193], v[26:29]
	v_mfma_f32_16x16x32_bf16 v[10:13], v[138:141], v[208:211], v[10:13]
	v_mfma_f32_16x16x32_bf16 v[10:13], v[142:145], v[212:215], v[10:13]
	v_mfma_f32_16x16x32_bf16 v[14:17], v[134:137], v[212:215], v[14:17]
	v_mfma_f32_16x16x32_bf16 v[14:17], v[130:133], v[208:211], v[14:17]
	v_mfma_f32_16x16x32_bf16 v[54:57], v[146:149], v[174:177], v[54:57]
	v_mfma_f32_16x16x32_bf16 v[54:57], v[162:165], v[178:181], v[54:57]
	v_mfma_f32_16x16x32_bf16 v[50:53], v[170:173], v[178:181], v[50:53]
	v_mfma_f32_16x16x32_bf16 v[50:53], v[166:169], v[174:177], v[50:53]
	v_mfma_f32_16x16x32_bf16 v[34:37], v[166:169], v[182:185], v[34:37]
	v_mfma_f32_16x16x32_bf16 v[34:37], v[170:173], v[186:189], v[34:37]
	v_mfma_f32_16x16x32_bf16 v[38:41], v[162:165], v[186:189], v[38:41]
	v_mfma_f32_16x16x32_bf16 v[38:41], v[146:149], v[182:185], v[38:41]
	v_mfma_f32_16x16x32_bf16 v[22:25], v[146:149], v[190:193], v[22:25]
	v_mfma_f32_16x16x32_bf16 v[22:25], v[162:165], v[204:207], v[22:25]
	v_mfma_f32_16x16x32_bf16 v[18:21], v[170:173], v[204:207], v[18:21]
	v_mfma_f32_16x16x32_bf16 v[18:21], v[166:169], v[190:193], v[18:21]
	v_mfma_f32_16x16x32_bf16 v[2:5], v[166:169], v[208:211], v[2:5]
	v_mfma_f32_16x16x32_bf16 v[2:5], v[170:173], v[212:215], v[2:5]
	v_mfma_f32_16x16x32_bf16 v[6:9], v[162:165], v[212:215], v[6:9]
	v_mfma_f32_16x16x32_bf16 v[6:9], v[146:149], v[208:211], v[6:9]
	s_setprio 0
	s_barrier
	s_mov_b32 m0, s38
	s_nop 0
	global_load_lds_dwordx4 v150, s[34:35]
	s_mov_b32 m0, s39
	s_nop 0
	global_load_lds_dwordx4 v154, s[34:35]
	ds_read_b128 v[130:133], v224 offset:32768
	ds_read_b128 v[134:137], v224 offset:33792
	ds_read_b128 v[138:141], v224 offset:34816
	ds_read_b128 v[142:145], v224 offset:35840
	ds_read_b128 v[146:149], v224 offset:49152
	ds_read_b128 v[162:165], v224 offset:50176
	ds_read_b128 v[166:169], v224 offset:51200
	ds_read_b128 v[170:173], v224 offset:52224
	ds_read_b128 v[174:177], v225 offset:32768
	ds_read_b128 v[178:181], v225 offset:33792
	ds_read_b128 v[182:185], v225 offset:34816
	ds_read_b128 v[186:189], v225 offset:35840
	ds_read_b128 v[190:193], v225 offset:36864
	ds_read_b128 v[204:207], v225 offset:37888
	ds_read_b128 v[208:211], v225 offset:38912
	ds_read_b128 v[212:215], v225 offset:39936
	s_add_i32 s58, 0, 0x18000
	s_add_i32 s59, 0, 0x1c000
	s_add_u32 s0, s34, 0x4000
	s_addc_u32 s1, s35, 0
	s_mov_b32 m0, s40
	s_nop 0
	global_load_lds_dwordx4 v150, s[0:1]
	s_mov_b32 m0, s41
	s_nop 0
	global_load_lds_dwordx4 v154, s[0:1]
	s_waitcnt vmcnt(8)
	s_waitcnt lgkmcnt(0)
	v_mfma_f32_16x16x32_bf16 v[126:129], v[130:133], v[174:177], v[126:129]
	v_mfma_f32_16x16x32_bf16 v[126:129], v[134:137], v[178:181], v[126:129]
	s_barrier
	s_setprio 1
	v_mfma_f32_16x16x32_bf16 v[122:125], v[142:145], v[178:181], v[122:125]
	v_mfma_f32_16x16x32_bf16 v[122:125], v[138:141], v[174:177], v[122:125]
	v_mfma_f32_16x16x32_bf16 v[106:109], v[138:141], v[182:185], v[106:109]
	v_mfma_f32_16x16x32_bf16 v[106:109], v[142:145], v[186:189], v[106:109]
	v_mfma_f32_16x16x32_bf16 v[110:113], v[134:137], v[186:189], v[110:113]
	v_mfma_f32_16x16x32_bf16 v[110:113], v[130:133], v[182:185], v[110:113]
	v_mfma_f32_16x16x32_bf16 v[94:97], v[130:133], v[190:193], v[94:97]
	v_mfma_f32_16x16x32_bf16 v[94:97], v[134:137], v[204:207], v[94:97]
	v_mfma_f32_16x16x32_bf16 v[90:93], v[142:145], v[204:207], v[90:93]
	v_mfma_f32_16x16x32_bf16 v[90:93], v[138:141], v[190:193], v[90:93]
	v_mfma_f32_16x16x32_bf16 v[74:77], v[138:141], v[208:211], v[74:77]
	v_mfma_f32_16x16x32_bf16 v[74:77], v[142:145], v[212:215], v[74:77]
	v_mfma_f32_16x16x32_bf16 v[78:81], v[134:137], v[212:215], v[78:81]
	v_mfma_f32_16x16x32_bf16 v[78:81], v[130:133], v[208:211], v[78:81]
	v_mfma_f32_16x16x32_bf16 v[118:121], v[146:149], v[174:177], v[118:121]
	v_mfma_f32_16x16x32_bf16 v[118:121], v[162:165], v[178:181], v[118:121]
	v_mfma_f32_16x16x32_bf16 v[114:117], v[170:173], v[178:181], v[114:117]
	v_mfma_f32_16x16x32_bf16 v[114:117], v[166:169], v[174:177], v[114:117]
	v_mfma_f32_16x16x32_bf16 v[98:101], v[166:169], v[182:185], v[98:101]
	v_mfma_f32_16x16x32_bf16 v[98:101], v[170:173], v[186:189], v[98:101]
	v_mfma_f32_16x16x32_bf16 v[102:105], v[162:165], v[186:189], v[102:105]
	v_mfma_f32_16x16x32_bf16 v[102:105], v[146:149], v[182:185], v[102:105]
	v_mfma_f32_16x16x32_bf16 v[86:89], v[146:149], v[190:193], v[86:89]
	v_mfma_f32_16x16x32_bf16 v[86:89], v[162:165], v[204:207], v[86:89]
	v_mfma_f32_16x16x32_bf16 v[82:85], v[170:173], v[204:207], v[82:85]
	v_mfma_f32_16x16x32_bf16 v[82:85], v[166:169], v[190:193], v[82:85]
	v_mfma_f32_16x16x32_bf16 v[66:69], v[166:169], v[208:211], v[66:69]
	v_mfma_f32_16x16x32_bf16 v[66:69], v[170:173], v[212:215], v[66:69]
	v_mfma_f32_16x16x32_bf16 v[70:73], v[162:165], v[212:215], v[70:73]
	v_mfma_f32_16x16x32_bf16 v[70:73], v[146:149], v[208:211], v[70:73]
	s_setprio 0
	s_barrier
	ds_read_b128 v[174:177], v225 offset:49152
	ds_read_b128 v[178:181], v225 offset:50176
	ds_read_b128 v[182:185], v225 offset:51200
	ds_read_b128 v[186:189], v225 offset:52224
	ds_read_b128 v[190:193], v225 offset:53248
	ds_read_b128 v[204:207], v225 offset:54272
	ds_read_b128 v[208:211], v225 offset:55296
	ds_read_b128 v[212:215], v225 offset:56320
	s_add_i32 s0, s58, s15
	s_add_u32 vcc_lo, s30, s94
	s_addc_u32 vcc_hi, s31, s95
	s_mov_b32 m0, s0
	s_nop 0
	global_load_lds_dwordx4 v152, vcc
	s_add_i32 m0, s0, 0x2000
	s_add_u32 s0, s30, 0x80080
	s_addc_u32 s1, s31, 0
	s_add_i32 s30, s59, s15
	global_load_lds_dwordx4 v156, vcc
	s_mov_b32 m0, s30
	s_nop 0
	global_load_lds_dwordx4 v152, s[0:1]
	s_add_i32 m0, s30, 0x2000
	s_nop 0
	global_load_lds_dwordx4 v156, s[0:1]
	s_waitcnt vmcnt(6)
	s_waitcnt lgkmcnt(0)
	v_mfma_f32_16x16x32_bf16 v[62:65], v[130:133], v[174:177], v[62:65]
	v_mfma_f32_16x16x32_bf16 v[62:65], v[134:137], v[178:181], v[62:65]
	s_barrier
	s_setprio 1
	v_mfma_f32_16x16x32_bf16 v[58:61], v[142:145], v[178:181], v[58:61]
	v_mfma_f32_16x16x32_bf16 v[58:61], v[138:141], v[174:177], v[58:61]
	v_mfma_f32_16x16x32_bf16 v[42:45], v[138:141], v[182:185], v[42:45]
	v_mfma_f32_16x16x32_bf16 v[42:45], v[142:145], v[186:189], v[42:45]
	v_mfma_f32_16x16x32_bf16 v[46:49], v[134:137], v[186:189], v[46:49]
	v_mfma_f32_16x16x32_bf16 v[46:49], v[130:133], v[182:185], v[46:49]
	v_mfma_f32_16x16x32_bf16 v[30:33], v[130:133], v[190:193], v[30:33]
	v_mfma_f32_16x16x32_bf16 v[30:33], v[134:137], v[204:207], v[30:33]
	v_mfma_f32_16x16x32_bf16 v[26:29], v[142:145], v[204:207], v[26:29]
	v_mfma_f32_16x16x32_bf16 v[26:29], v[138:141], v[190:193], v[26:29]
	v_mfma_f32_16x16x32_bf16 v[10:13], v[138:141], v[208:211], v[10:13]
	v_mfma_f32_16x16x32_bf16 v[10:13], v[142:145], v[212:215], v[10:13]
	s_add_i32 s57, s57, 2
	v_mfma_f32_16x16x32_bf16 v[14:17], v[134:137], v[212:215], v[14:17]
	v_mfma_f32_16x16x32_bf16 v[14:17], v[130:133], v[208:211], v[14:17]
	s_add_u32 s50, s50, 0x100
	v_mfma_f32_16x16x32_bf16 v[54:57], v[146:149], v[174:177], v[54:57]
	v_mfma_f32_16x16x32_bf16 v[54:57], v[162:165], v[178:181], v[54:57]
	s_addc_u32 s51, s51, 0
	v_mfma_f32_16x16x32_bf16 v[50:53], v[170:173], v[178:181], v[50:53]
	v_mfma_f32_16x16x32_bf16 v[50:53], v[166:169], v[174:177], v[50:53]
	s_cmp_gt_u32 s57, 29
	v_mfma_f32_16x16x32_bf16 v[34:37], v[166:169], v[182:185], v[34:37]
	v_mfma_f32_16x16x32_bf16 v[34:37], v[170:173], v[186:189], v[34:37]
	s_mov_b64 s[0:1], s[4:5]
	v_mfma_f32_16x16x32_bf16 v[38:41], v[162:165], v[186:189], v[38:41]
	v_mfma_f32_16x16x32_bf16 v[38:41], v[146:149], v[182:185], v[38:41]
	v_mfma_f32_16x16x32_bf16 v[22:25], v[146:149], v[190:193], v[22:25]
	v_mfma_f32_16x16x32_bf16 v[22:25], v[162:165], v[204:207], v[22:25]
	v_mfma_f32_16x16x32_bf16 v[18:21], v[170:173], v[204:207], v[18:21]
	v_mfma_f32_16x16x32_bf16 v[18:21], v[166:169], v[190:193], v[18:21]
	v_mfma_f32_16x16x32_bf16 v[2:5], v[166:169], v[208:211], v[2:5]
	v_mfma_f32_16x16x32_bf16 v[2:5], v[170:173], v[212:215], v[2:5]
	v_mfma_f32_16x16x32_bf16 v[6:9], v[162:165], v[212:215], v[6:9]
	v_mfma_f32_16x16x32_bf16 v[6:9], v[146:149], v[208:211], v[6:9]
	s_setprio 0
	s_barrier
	s_cbranch_scc0 .LBB0_133
.LBB0_136:
	s_and_b64 vcc, exec, s[2:3]
	s_and_b32 s50, s33, 1
	s_cbranch_vccnz .LBB0_141
	v_mov_b32_e32 v131, v0
	s_mov_b32 s25, s24
	v_readfirstlane_b32 s4, v131
	s_ashr_i32 s1, s4, 8
	s_bfe_u32 s5, s4, 0x20006
	s_mov_b32 s4, s56
	s_xor_b32 s0, s50, 1
	s_add_i32 s30, s25, -16
	s_cmp_gt_u32 s30, 23
	v_and_b32_e32 v130, 63, v131
	s_cbranch_scc1 .LBB0_139
	s_lshl_b32 s25, s25, 8
	v_lshlrev_b32_e32 v132, 2, v130
	s_addk_i32 s25, 0xf000
	v_and_b32_e32 v132, 0x80, v132
	v_and_b32_e32 v131, 31, v131
	v_or_b32_e32 v132, s25, v132
	s_lshl_b32 s25, s5, 5
	s_lshl_b32 s30, s1, 2
	v_or3_b32 v194, v132, s25, v131
	s_mul_i32 s25, s0, 0x3000
	s_or_b32 s30, s30, s5
	s_add_i32 s25, s25, 0
	s_mulk_i32 s30, 0x600
	s_add_i32 s25, s25, s30
	v_lshlrev_b64 v[132:133], 2, v[194:195]
	s_add_i32 m0, s25, 0x20000
	v_lshl_add_u64 v[134:135], s[6:7], 0, v[132:133]
	global_load_lds_dword v[134:135], off
	v_lshl_add_u64 v[134:135], s[18:19], 0, v[132:133]
	s_add_i32 m0, s25, 0x20100
	s_nop 0
	global_load_lds_dword v[134:135], off
	v_lshl_add_u64 v[134:135], s[20:21], 0, v[132:133]
	s_add_i32 m0, s25, 0x20200
	s_nop 0
	global_load_lds_dword v[134:135], off
	v_lshl_add_u64 v[134:135], s[22:23], 0, v[132:133]
	s_add_i32 m0, s25, 0x20300
	v_lshl_add_u64 v[132:133], s[8:9], 0, v[132:133]
	global_load_lds_dword v[134:135], off
	s_add_i32 m0, s25, 0x20400
	s_nop 0
	global_load_lds_dword v[132:133], off

.LBB0_141:
	v_mov_b32_e32 v146, v0
	s_lshl_b32 s1, s50, 11
	v_readfirstlane_b32 s0, v146
	s_ashr_i32 s51, s0, 8
	s_add_i32 s1, s1, 0
	s_lshl_b32 s4, s51, 10
	v_and_b32_e32 v226, 15, v146
	s_add_i32 s1, s1, s4
	v_lshl_add_u32 v130, v226, 6, s1
	v_add_u32_e32 v142, 0x26000, v130
	ds_read_b128 v[130:133], v142
	ds_read_b128 v[134:137], v142 offset:16
	s_and_b64 vcc, exec, s[16:17]
	s_cbranch_vccz .Lalign_l0
	s_barrier
.Lalign_l0:
	s_bfe_u32 s33, s0, 0x20006
	s_mul_i32 s0, s36, 0xfa
	s_mul_i32 s1, s51, 0x7d
	s_waitcnt lgkmcnt(0)
	v_ffbh_u32_e32 v138, v131
	v_min_u32_e32 v147, 32, v138
	v_lshlrev_b64 v[130:131], v147, v[130:131]
	v_min_u32_e32 v130, 1, v130
	v_or_b32_e32 v130, v131, v130
	v_cvt_f32_u32_e32 v130, v130
	v_sub_u32_e32 v131, 32, v147
	ds_read_b128 v[138:141], v142 offset:32
	ds_read_b128 v[142:145], v142 offset:48
	s_add_i32 s25, s0, s1
	v_ldexp_f32 v147, v130, v131
	v_ffbh_u32_e32 v130, v133
	v_min_u32_e32 v148, 32, v130
	v_lshlrev_b64 v[130:131], v148, v[132:133]
	v_min_u32_e32 v130, 1, v130
	v_or_b32_e32 v130, v131, v130
	v_cvt_f32_u32_e32 v130, v130
	v_fmamk_f32 v131, v147, 0x30000000, v1
	v_rsq_f32_e32 v176, v131
	v_sub_u32_e32 v131, 32, v148
	v_ldexp_f32 v132, v130, v131
	v_ffbh_u32_e32 v130, v135
	v_min_u32_e32 v133, 32, v130
	v_lshlrev_b64 v[130:131], v133, v[134:135]
	v_min_u32_e32 v130, 1, v130
	v_or_b32_e32 v130, v131, v130
	v_cvt_f32_u32_e32 v130, v130
	v_fmamk_f32 v131, v132, 0x30000000, v1
	v_rsq_f32_e32 v174, v131
	v_sub_u32_e32 v131, 32, v133
	v_ldexp_f32 v132, v130, v131
	v_ffbh_u32_e32 v130, v137
	v_min_u32_e32 v133, 32, v130
	v_lshlrev_b64 v[130:131], v133, v[136:137]
	v_min_u32_e32 v130, 1, v130
	v_or_b32_e32 v130, v131, v130
	v_cvt_f32_u32_e32 v130, v130
	v_fmamk_f32 v131, v132, 0x30000000, v1
	v_rsq_f32_e32 v172, v131
	v_sub_u32_e32 v131, 32, v133
	v_ldexp_f32 v132, v130, v131
	s_waitcnt lgkmcnt(0)
	v_ffbh_u32_e32 v130, v139
	v_min_u32_e32 v133, 32, v130
	v_lshlrev_b64 v[130:131], v133, v[138:139]
	v_min_u32_e32 v130, 1, v130
	v_or_b32_e32 v130, v131, v130
	v_cvt_f32_u32_e32 v130, v130
	v_fmamk_f32 v131, v132, 0x30000000, v1
	v_rsq_f32_e32 v170, v131
	v_sub_u32_e32 v131, 32, v133
	v_ldexp_f32 v132, v130, v131
	v_ffbh_u32_e32 v130, v141
	v_min_u32_e32 v133, 32, v130
	v_lshlrev_b64 v[130:131], v133, v[140:141]
	v_min_u32_e32 v130, 1, v130
	v_or_b32_e32 v130, v131, v130
	v_cvt_f32_u32_e32 v130, v130
	v_fmamk_f32 v131, v132, 0x30000000, v1
	v_rsq_f32_e32 v168, v131
	v_sub_u32_e32 v131, 32, v133
	v_ldexp_f32 v132, v130, v131
	v_ffbh_u32_e32 v130, v143
	v_min_u32_e32 v133, 32, v130
	v_lshlrev_b64 v[130:131], v133, v[142:143]
	v_min_u32_e32 v130, 1, v130
	v_or_b32_e32 v130, v131, v130
	v_cvt_f32_u32_e32 v130, v130
	v_fmamk_f32 v131, v132, 0x30000000, v1
	v_rsq_f32_e32 v166, v131
	v_sub_u32_e32 v131, 32, v133
	v_ldexp_f32 v132, v130, v131
	v_ffbh_u32_e32 v130, v145
	v_min_u32_e32 v133, 32, v130
	v_lshlrev_b64 v[130:131], v133, v[144:145]
	v_min_u32_e32 v130, 1, v130
	v_or_b32_e32 v130, v131, v130
	v_cvt_f32_u32_e32 v130, v130
	v_fmamk_f32 v131, v132, 0x30000000, v1
	v_rsq_f32_e32 v164, v131
	v_sub_u32_e32 v131, 32, v133
	v_ldexp_f32 v130, v130, v131
	v_fmamk_f32 v130, v130, 0x30000000, v1
	v_rsq_f32_e32 v162, v130
	s_add_i32 s25, s25, -3
	v_bfe_u32 v228, v146, 4, 2
	v_lshl_add_u32 v227, v226, 3, s25
	s_cmp_gt_i32 s14, 15
	s_mov_b64 s[0:1], -1
	s_cbranch_scc1 .LBB0_144
	s_andn2_b64 vcc, exec, s[0:1]
	s_cbranch_vccz .LBB0_239

.LBB0_533:
	v_lshl_add_u32 v158, s33, 8, v143
	v_ashrrev_i32_e32 v159, 31, v158
	v_lshl_add_u64 v[152:153], v[158:159], 3, s[4:5]
	global_load_dwordx2 v[154:155], v[152:153], off
	global_load_dwordx2 v[162:163], v[152:153], off offset:128
	global_load_dwordx2 v[164:165], v[152:153], off offset:256
	global_load_dwordx2 v[166:167], v[152:153], off offset:384
	global_load_dwordx2 v[168:169], v[152:153], off offset:1024
	global_load_dwordx2 v[170:171], v[152:153], off offset:1152
	global_load_dwordx2 v[172:173], v[152:153], off offset:1280
	global_load_dwordx2 v[174:175], v[152:153], off offset:1408
	s_and_b64 vcc, exec, s[6:7]
	s_cbranch_vccz .Lalign_l2
	s_barrier
.Lalign_l2:
	v_add_u32_e32 v160, 0x80, v158
	v_ashrrev_i32_e32 v161, 31, v160
	s_mov_b64 s[14:15], -1
	s_cmp_lt_i32 s31, 8
	v_lshlrev_b64 v[160:161], 12, v[160:161]
	s_waitcnt vmcnt(0)
	v_ffbh_u32_e32 v142, v155
	v_min_u32_e32 v142, 32, v142
	v_lshlrev_b64 v[152:153], v142, v[154:155]
	v_min_u32_e32 v144, 1, v152
	v_or_b32_e32 v144, v153, v144
	v_cvt_f32_u32_e32 v144, v144
	v_sub_u32_e32 v142, 32, v142
	v_ldexp_f32 v142, v144, v142
	v_fmamk_f32 v142, v142, 0x30000000, v1
	v_rsq_f32_e32 v156, v142
	v_ffbh_u32_e32 v142, v163
	v_min_u32_e32 v142, 32, v142
	v_lshlrev_b64 v[152:153], v142, v[162:163]
	v_min_u32_e32 v144, 1, v152
	v_or_b32_e32 v144, v153, v144
	v_cvt_f32_u32_e32 v144, v144
	v_sub_u32_e32 v142, 32, v142
	v_ldexp_f32 v142, v144, v142
	v_fmamk_f32 v142, v142, 0x30000000, v1
	v_rsq_f32_e32 v154, v142
	v_ffbh_u32_e32 v142, v165
	v_min_u32_e32 v142, 32, v142
	v_lshlrev_b64 v[152:153], v142, v[164:165]
	v_min_u32_e32 v144, 1, v152
	v_or_b32_e32 v144, v153, v144
	v_cvt_f32_u32_e32 v144, v144
	v_sub_u32_e32 v142, 32, v142
	v_or_b32_e32 v164, 16, v158
	v_ldexp_f32 v142, v144, v142
	v_fmamk_f32 v142, v142, 0x30000000, v1
	v_rsq_f32_e32 v152, v142
	v_ffbh_u32_e32 v142, v167
	v_min_u32_e32 v142, 32, v142
	v_lshlrev_b64 v[162:163], v142, v[166:167]
	v_min_u32_e32 v144, 1, v162
	v_or_b32_e32 v144, v163, v144
	v_cvt_f32_u32_e32 v144, v144
	v_sub_u32_e32 v142, 32, v142
	v_lshlrev_b64 v[166:167], 12, v[158:159]
	v_ldexp_f32 v142, v144, v142
	v_fmamk_f32 v142, v142, 0x30000000, v1
	v_rsq_f32_e32 v150, v142
	v_ffbh_u32_e32 v142, v169
	v_min_u32_e32 v142, 32, v142
	v_lshlrev_b64 v[162:163], v142, v[168:169]
	v_min_u32_e32 v144, 1, v162
	v_or_b32_e32 v144, v163, v144
	v_cvt_f32_u32_e32 v144, v144
	v_sub_u32_e32 v142, 32, v142
	v_ldexp_f32 v142, v144, v142
	v_fmamk_f32 v142, v142, 0x30000000, v1
	v_rsq_f32_e32 v148, v142
	v_ffbh_u32_e32 v142, v171
	v_min_u32_e32 v142, 32, v142
	v_lshlrev_b64 v[162:163], v142, v[170:171]
	v_min_u32_e32 v144, 1, v162
	v_or_b32_e32 v144, v163, v144
	v_cvt_f32_u32_e32 v144, v144
	v_sub_u32_e32 v142, 32, v142
	v_ldexp_f32 v142, v144, v142
	v_fmamk_f32 v142, v142, 0x30000000, v1
	v_rsq_f32_e32 v146, v142
	v_ffbh_u32_e32 v142, v173
	v_min_u32_e32 v142, 32, v142
	v_lshlrev_b64 v[162:163], v142, v[172:173]
	v_min_u32_e32 v144, 1, v162
	v_or_b32_e32 v144, v163, v144
	v_cvt_f32_u32_e32 v144, v144
	v_sub_u32_e32 v142, 32, v142
	v_ldexp_f32 v142, v144, v142
	v_fmamk_f32 v142, v142, 0x30000000, v1
	v_rsq_f32_e32 v144, v142
	v_ffbh_u32_e32 v142, v175
	v_min_u32_e32 v142, 32, v142
	v_lshlrev_b64 v[162:163], v142, v[174:175]
	v_min_u32_e32 v153, 1, v162
	v_or_b32_e32 v153, v163, v153
	v_cvt_f32_u32_e32 v153, v153
	v_sub_u32_e32 v142, 32, v142
	v_or_b32_e32 v162, 32, v158
	v_or_b32_e32 v158, 48, v158
	v_ldexp_f32 v142, v153, v142
	v_fmamk_f32 v142, v142, 0x30000000, v1
	v_rsq_f32_e32 v142, v142
	s_cbranch_scc0 .LBB0_536
	s_andn2_b64 vcc, exec, s[14:15]
	s_cbranch_vccz .LBB0_537

.LBB0_853:
	v_lshl_or_b32 v66, s39, 8, v199
	v_lshl_add_u32 v214, s50, 8, v197
	v_ashrrev_i32_e32 v67, 31, v66
	v_lshlrev_b64 v[216:217], 1, v[66:67]
	v_ashrrev_i32_e32 v215, 31, v214
	v_lshl_add_u64 v[66:67], s[86:87], 0, v[216:217]
	v_lshlrev_b64 v[232:233], 12, v[214:215]
	v_lshl_add_u64 v[68:69], v[66:67], 0, v[232:233]
	global_load_dwordx4 v[190:193], v[68:69], off
	global_load_dwordx4 v[178:181], v[68:69], off offset:256
	v_or_b32_e32 v68, 16, v214
	v_ashrrev_i32_e32 v69, 31, v68
	v_lshlrev_b64 v[230:231], 12, v[68:69]
	v_lshl_add_u64 v[68:69], v[66:67], 0, v[230:231]
	global_load_dwordx4 v[174:177], v[68:69], off
	global_load_dwordx4 v[170:173], v[68:69], off offset:256
	v_or_b32_e32 v68, 32, v214
	v_ashrrev_i32_e32 v69, 31, v68
	v_lshlrev_b64 v[228:229], 12, v[68:69]
	v_lshl_add_u64 v[68:69], v[66:67], 0, v[228:229]
	global_load_dwordx4 v[162:165], v[68:69], off
	global_load_dwordx4 v[158:161], v[68:69], off offset:256
	v_or_b32_e32 v68, 48, v214
	v_ashrrev_i32_e32 v69, 31, v68
	v_lshlrev_b64 v[226:227], 12, v[68:69]
	v_lshl_add_u64 v[68:69], v[66:67], 0, v[226:227]
	global_load_dwordx4 v[154:157], v[68:69], off
	global_load_dwordx4 v[150:153], v[68:69], off offset:256
	s_mov_b64 s[18:19], 0x80000
	v_lshl_add_u64 v[224:225], v[232:233], 0, s[18:19]
	s_mov_b64 s[18:19], 0x90000
	v_lshl_add_u64 v[222:223], v[232:233], 0, s[18:19]
	s_mov_b64 s[18:19], 0xa0000
	v_lshl_add_u64 v[68:69], v[66:67], 0, v[224:225]
	v_lshl_add_u64 v[220:221], v[232:233], 0, s[18:19]
	s_mov_b64 s[18:19], 0xb0000
	global_load_dwordx4 v[142:145], v[68:69], off
	global_load_dwordx4 v[130:133], v[68:69], off offset:256
	v_lshl_add_u64 v[68:69], v[66:67], 0, v[222:223]
	v_lshl_add_u64 v[218:219], v[232:233], 0, s[18:19]
	v_lshl_add_u64 v[232:233], s[86:87], 0, v[232:233]
	global_load_dwordx4 v[118:121], v[68:69], off
	global_load_dwordx4 v[106:109], v[68:69], off offset:256
	v_lshl_add_u64 v[68:69], v[66:67], 0, v[220:221]
	v_lshl_add_u64 v[66:67], v[66:67], 0, v[218:219]
	v_lshl_add_u64 v[232:233], v[232:233], 0, v[216:217]
	global_load_dwordx4 v[98:101], v[68:69], off
	global_load_dwordx4 v[82:85], v[68:69], off offset:256
	global_load_dwordx4 v[78:81], v[66:67], off
	s_nop 0
	global_load_dwordx4 v[66:69], v[66:67], off offset:256
	s_and_b64 vcc, exec, s[14:15]
	s_cbranch_vccz .Lalign_l5
	s_barrier
.Lalign_l5:
	s_movk_i32 s18, 0x80
	s_waitcnt vmcnt(0)
	v_lshlrev_b32_e32 v236, 16, v190
	v_and_b32_e32 v237, 0xffff0000, v190
	v_lshlrev_b32_e32 v190, 16, v191
	v_and_b32_e32 v191, 0xffff0000, v191
	v_pk_add_f32 v[186:187], v[186:187], v[236:237]
	v_pk_add_f32 v[188:189], v[188:189], v[190:191]
	v_cvt_pk_bf16_f32 v186, v186, v187
	v_cvt_pk_bf16_f32 v187, v188, v189
	v_lshlrev_b32_e32 v188, 16, v192
	v_and_b32_e32 v189, 0xffff0000, v192
	v_pk_add_f32 v[182:183], v[182:183], v[188:189]
	s_nop 0
	v_cvt_pk_bf16_f32 v188, v182, v183
	v_lshlrev_b32_e32 v182, 16, v193
	v_and_b32_e32 v183, 0xffff0000, v193
	v_pk_add_f32 v[182:183], v[184:185], v[182:183]
	v_and_b32_e32 v185, 0xffff0000, v187
	v_cvt_pk_bf16_f32 v189, v182, v183
	v_and_b32_e32 v183, 0xffff0000, v186
	v_lshlrev_b32_e32 v182, 16, v186
	v_mul_f32_e32 v183, v183, v183
	v_lshlrev_b32_e32 v184, 16, v187
	v_fmac_f32_e32 v183, v182, v182
	v_mul_f32_e32 v182, v185, v185
	global_store_dwordx4 v[232:233], v[186:189], off
	v_fmac_f32_e32 v182, v184, v184
	v_add_f32_e32 v182, v183, v182
	v_lshlrev_b32_e32 v186, 16, v188
	v_and_b32_e32 v187, 0xffff0000, v188
	v_lshlrev_b32_e32 v188, 16, v189
	v_and_b32_e32 v189, 0xffff0000, v189
	v_mul_f32_e32 v183, v187, v187
	v_mul_f32_e32 v184, v189, v189
	v_fmac_f32_e32 v183, v186, v186
	v_fmac_f32_e32 v184, v188, v188
	v_add_f32_e32 v183, v183, v184
	v_add_f32_e32 v184, v182, v183
	v_lshlrev_b32_e32 v182, 16, v178
	v_and_b32_e32 v183, 0xffff0000, v178
	v_lshlrev_b32_e32 v178, 16, v179
	v_and_b32_e32 v179, 0xffff0000, v179
	v_pk_add_f32 v[166:167], v[166:167], v[182:183]
	v_pk_add_f32 v[168:169], v[168:169], v[178:179]
	v_cvt_pk_bf16_f32 v166, v166, v167
	v_cvt_pk_bf16_f32 v167, v168, v169
	v_lshlrev_b32_e32 v168, 16, v180
	v_and_b32_e32 v169, 0xffff0000, v180
	v_pk_add_f32 v[146:147], v[146:147], v[168:169]
	s_nop 0
	v_cvt_pk_bf16_f32 v168, v146, v147
	v_lshlrev_b32_e32 v146, 16, v181
	v_and_b32_e32 v147, 0xffff0000, v181
	v_pk_add_f32 v[146:147], v[148:149], v[146:147]
	v_and_b32_e32 v149, 0xffff0000, v167
	v_cvt_pk_bf16_f32 v169, v146, v147
	v_and_b32_e32 v147, 0xffff0000, v166
	v_lshlrev_b32_e32 v146, 16, v166
	v_mul_f32_e32 v147, v147, v147
	v_lshlrev_b32_e32 v148, 16, v167
	v_fmac_f32_e32 v147, v146, v146
	v_mul_f32_e32 v146, v149, v149
	global_store_dwordx4 v[232:233], v[166:169], off offset:256
	v_fmac_f32_e32 v146, v148, v148
	v_add_f32_e32 v146, v147, v146
	v_and_b32_e32 v167, 0xffff0000, v168
	v_lshlrev_b32_e32 v166, 16, v168
	v_mul_f32_e32 v147, v167, v167
	v_fmac_f32_e32 v147, v166, v166
	v_lshlrev_b32_e32 v166, 16, v174
	v_and_b32_e32 v167, 0xffff0000, v174
	v_pk_add_f32 v[138:139], v[138:139], v[166:167]
	v_lshlrev_b32_e32 v166, 16, v175
	v_and_b32_e32 v167, 0xffff0000, v175
	v_pk_add_f32 v[140:141], v[140:141], v[166:167]
	v_cvt_pk_bf16_f32 v138, v138, v139
	v_cvt_pk_bf16_f32 v139, v140, v141
	v_lshlrev_b32_e32 v140, 16, v176
	v_and_b32_e32 v141, 0xffff0000, v176
	v_pk_add_f32 v[134:135], v[134:135], v[140:141]
	v_lshlrev_b32_e32 v168, 16, v169
	v_and_b32_e32 v169, 0xffff0000, v169
	v_cvt_pk_bf16_f32 v140, v134, v135
	v_lshlrev_b32_e32 v134, 16, v177
	v_and_b32_e32 v135, 0xffff0000, v177
	v_mul_f32_e32 v148, v169, v169
	v_pk_add_f32 v[134:135], v[136:137], v[134:135]
	v_fmac_f32_e32 v148, v168, v168
	v_cvt_pk_bf16_f32 v141, v134, v135
	v_and_b32_e32 v135, 0xffff0000, v138
	v_add_f32_e32 v147, v147, v148
	v_lshl_add_u64 v[148:149], s[86:87], 0, v[230:231]
	v_lshlrev_b32_e32 v134, 16, v138
	v_and_b32_e32 v137, 0xffff0000, v139
	v_mul_f32_e32 v135, v135, v135
	v_lshl_add_u64 v[148:149], v[148:149], 0, v[216:217]
	v_lshlrev_b32_e32 v136, 16, v139
	v_fmac_f32_e32 v135, v134, v134
	v_mul_f32_e32 v134, v137, v137
	global_store_dwordx4 v[148:149], v[138:141], off
	v_fmac_f32_e32 v134, v136, v136
	v_add_f32_e32 v134, v135, v134
	v_lshlrev_b32_e32 v138, 16, v140
	v_and_b32_e32 v139, 0xffff0000, v140
	v_lshlrev_b32_e32 v140, 16, v141
	v_and_b32_e32 v141, 0xffff0000, v141
	v_mul_f32_e32 v135, v139, v139
	v_mul_f32_e32 v136, v141, v141
	v_fmac_f32_e32 v135, v138, v138
	v_fmac_f32_e32 v136, v140, v140
	v_add_f32_e32 v135, v135, v136
	v_add_f32_e32 v136, v134, v135
	v_lshlrev_b32_e32 v134, 16, v170
	v_and_b32_e32 v135, 0xffff0000, v170
	v_pk_add_f32 v[126:127], v[126:127], v[134:135]
	v_lshlrev_b32_e32 v134, 16, v171
	v_and_b32_e32 v135, 0xffff0000, v171
	v_pk_add_f32 v[128:129], v[128:129], v[134:135]
	v_cvt_pk_bf16_f32 v126, v126, v127
	v_cvt_pk_bf16_f32 v127, v128, v129
	v_lshlrev_b32_e32 v128, 16, v172
	v_and_b32_e32 v129, 0xffff0000, v172
	v_pk_add_f32 v[122:123], v[122:123], v[128:129]
	v_add_f32_e32 v146, v146, v147
	v_cvt_pk_bf16_f32 v128, v122, v123
	v_lshlrev_b32_e32 v122, 16, v173
	v_and_b32_e32 v123, 0xffff0000, v173
	v_pk_add_f32 v[122:123], v[124:125], v[122:123]
	v_and_b32_e32 v125, 0xffff0000, v127
	v_cvt_pk_bf16_f32 v129, v122, v123
	v_and_b32_e32 v123, 0xffff0000, v126
	v_lshlrev_b32_e32 v122, 16, v126
	v_mul_f32_e32 v123, v123, v123
	v_lshlrev_b32_e32 v124, 16, v127
	v_fmac_f32_e32 v123, v122, v122
	v_mul_f32_e32 v122, v125, v125
	global_store_dwordx4 v[148:149], v[126:129], off offset:256
	v_fmac_f32_e32 v122, v124, v124
	v_add_f32_e32 v122, v123, v122
	v_and_b32_e32 v127, 0xffff0000, v128
	v_lshlrev_b32_e32 v126, 16, v128
	v_mul_f32_e32 v123, v127, v127
	v_fmac_f32_e32 v123, v126, v126
	v_lshlrev_b32_e32 v126, 16, v162
	v_and_b32_e32 v127, 0xffff0000, v162
	v_pk_add_f32 v[114:115], v[114:115], v[126:127]
	v_lshlrev_b32_e32 v126, 16, v163
	v_and_b32_e32 v127, 0xffff0000, v163
	v_pk_add_f32 v[116:117], v[116:117], v[126:127]
	v_cvt_pk_bf16_f32 v114, v114, v115
	v_cvt_pk_bf16_f32 v115, v116, v117
	v_lshlrev_b32_e32 v116, 16, v164
	v_and_b32_e32 v117, 0xffff0000, v164
	v_pk_add_f32 v[110:111], v[110:111], v[116:117]
	v_lshlrev_b32_e32 v128, 16, v129
	v_and_b32_e32 v129, 0xffff0000, v129
	v_cvt_pk_bf16_f32 v116, v110, v111
	v_lshlrev_b32_e32 v110, 16, v165
	v_and_b32_e32 v111, 0xffff0000, v165
	v_mul_f32_e32 v124, v129, v129
	v_pk_add_f32 v[110:111], v[112:113], v[110:111]
	v_fmac_f32_e32 v124, v128, v128
	v_cvt_pk_bf16_f32 v117, v110, v111
	v_and_b32_e32 v111, 0xffff0000, v114
	v_add_f32_e32 v123, v123, v124
	v_lshl_add_u64 v[124:125], s[86:87], 0, v[228:229]
	v_lshlrev_b32_e32 v110, 16, v114
	v_and_b32_e32 v113, 0xffff0000, v115
	v_mul_f32_e32 v111, v111, v111
	v_lshl_add_u64 v[124:125], v[124:125], 0, v[216:217]
	v_lshlrev_b32_e32 v112, 16, v115
	v_fmac_f32_e32 v111, v110, v110
	v_mul_f32_e32 v110, v113, v113
	global_store_dwordx4 v[124:125], v[114:117], off
	v_fmac_f32_e32 v110, v112, v112
	v_add_f32_e32 v110, v111, v110
	v_lshlrev_b32_e32 v114, 16, v116
	v_and_b32_e32 v115, 0xffff0000, v116
	v_lshlrev_b32_e32 v116, 16, v117
	v_and_b32_e32 v117, 0xffff0000, v117
	v_mul_f32_e32 v111, v115, v115
	v_mul_f32_e32 v112, v117, v117
	v_fmac_f32_e32 v111, v114, v114
	v_fmac_f32_e32 v112, v116, v116
	v_add_f32_e32 v111, v111, v112
	v_add_f32_e32 v112, v110, v111
	v_lshlrev_b32_e32 v110, 16, v158
	v_and_b32_e32 v111, 0xffff0000, v158
	v_pk_add_f32 v[102:103], v[102:103], v[110:111]
	v_lshlrev_b32_e32 v110, 16, v159
	v_and_b32_e32 v111, 0xffff0000, v159
	v_pk_add_f32 v[104:105], v[104:105], v[110:111]
	v_cvt_pk_bf16_f32 v102, v102, v103
	v_cvt_pk_bf16_f32 v103, v104, v105
	v_lshlrev_b32_e32 v104, 16, v160
	v_and_b32_e32 v105, 0xffff0000, v160
	v_pk_add_f32 v[94:95], v[94:95], v[104:105]
	v_add_f32_e32 v122, v122, v123
	v_cvt_pk_bf16_f32 v104, v94, v95
	v_lshlrev_b32_e32 v94, 16, v161
	v_and_b32_e32 v95, 0xffff0000, v161
	v_pk_add_f32 v[94:95], v[96:97], v[94:95]
	v_and_b32_e32 v97, 0xffff0000, v103
	v_cvt_pk_bf16_f32 v105, v94, v95
	v_and_b32_e32 v95, 0xffff0000, v102
	v_lshlrev_b32_e32 v94, 16, v102
	v_mul_f32_e32 v95, v95, v95
	v_lshlrev_b32_e32 v96, 16, v103
	v_fmac_f32_e32 v95, v94, v94
	v_mul_f32_e32 v94, v97, v97
	global_store_dwordx4 v[124:125], v[102:105], off offset:256
	v_fmac_f32_e32 v94, v96, v96
	v_add_f32_e32 v94, v95, v94
	v_and_b32_e32 v103, 0xffff0000, v104
	v_lshlrev_b32_e32 v102, 16, v104
	v_mul_f32_e32 v95, v103, v103
	v_fmac_f32_e32 v95, v102, v102
	v_lshlrev_b32_e32 v102, 16, v154
	v_and_b32_e32 v103, 0xffff0000, v154
	v_pk_add_f32 v[90:91], v[90:91], v[102:103]
	v_lshlrev_b32_e32 v102, 16, v155
	v_and_b32_e32 v103, 0xffff0000, v155
	v_pk_add_f32 v[92:93], v[92:93], v[102:103]
	v_cvt_pk_bf16_f32 v90, v90, v91
	v_cvt_pk_bf16_f32 v91, v92, v93
	v_lshlrev_b32_e32 v92, 16, v156
	v_and_b32_e32 v93, 0xffff0000, v156
	v_pk_add_f32 v[86:87], v[86:87], v[92:93]
	v_lshlrev_b32_e32 v104, 16, v105
	v_and_b32_e32 v105, 0xffff0000, v105
	v_cvt_pk_bf16_f32 v92, v86, v87
	v_lshlrev_b32_e32 v86, 16, v157
	v_and_b32_e32 v87, 0xffff0000, v157
	v_mul_f32_e32 v96, v105, v105
	v_pk_add_f32 v[86:87], v[88:89], v[86:87]
	v_fmac_f32_e32 v96, v104, v104
	v_cvt_pk_bf16_f32 v93, v86, v87
	v_and_b32_e32 v87, 0xffff0000, v90
	v_add_f32_e32 v95, v95, v96
	v_lshl_add_u64 v[96:97], s[86:87], 0, v[226:227]
	v_lshlrev_b32_e32 v86, 16, v90
	v_and_b32_e32 v89, 0xffff0000, v91
	v_mul_f32_e32 v87, v87, v87
	v_lshl_add_u64 v[96:97], v[96:97], 0, v[216:217]
	v_lshlrev_b32_e32 v88, 16, v91
	v_fmac_f32_e32 v87, v86, v86
	v_mul_f32_e32 v86, v89, v89
	global_store_dwordx4 v[96:97], v[90:93], off
	v_fmac_f32_e32 v86, v88, v88
	v_add_f32_e32 v86, v87, v86
	v_lshlrev_b32_e32 v90, 16, v92
	v_and_b32_e32 v91, 0xffff0000, v92
	v_lshlrev_b32_e32 v92, 16, v93
	v_and_b32_e32 v93, 0xffff0000, v93
	v_mul_f32_e32 v87, v91, v91
	v_mul_f32_e32 v88, v93, v93
	v_fmac_f32_e32 v87, v90, v90
	v_fmac_f32_e32 v88, v92, v92
	v_add_f32_e32 v87, v87, v88
	v_add_f32_e32 v88, v86, v87
	v_lshlrev_b32_e32 v86, 16, v150
	v_and_b32_e32 v87, 0xffff0000, v150
	v_pk_add_f32 v[74:75], v[74:75], v[86:87]
	v_lshlrev_b32_e32 v86, 16, v151
	v_and_b32_e32 v87, 0xffff0000, v151
	v_pk_add_f32 v[76:77], v[76:77], v[86:87]
	v_cvt_pk_bf16_f32 v74, v74, v75
	v_cvt_pk_bf16_f32 v75, v76, v77
	v_lshlrev_b32_e32 v76, 16, v152
	v_and_b32_e32 v77, 0xffff0000, v152
	v_pk_add_f32 v[70:71], v[70:71], v[76:77]
	v_add_f32_e32 v94, v94, v95
	v_cvt_pk_bf16_f32 v76, v70, v71
	v_lshlrev_b32_e32 v70, 16, v153
	v_and_b32_e32 v71, 0xffff0000, v153
	v_pk_add_f32 v[70:71], v[72:73], v[70:71]
	v_and_b32_e32 v73, 0xffff0000, v75
	v_cvt_pk_bf16_f32 v77, v70, v71
	v_and_b32_e32 v71, 0xffff0000, v74
	v_lshlrev_b32_e32 v70, 16, v74
	v_mul_f32_e32 v71, v71, v71
	v_lshlrev_b32_e32 v72, 16, v75
	v_fmac_f32_e32 v71, v70, v70
	v_mul_f32_e32 v70, v73, v73
	global_store_dwordx4 v[96:97], v[74:77], off offset:256
	v_fmac_f32_e32 v70, v72, v72
	v_add_f32_e32 v70, v71, v70
	v_lshlrev_b32_e32 v74, 16, v76
	v_and_b32_e32 v75, 0xffff0000, v76
	v_lshlrev_b32_e32 v76, 16, v77
	v_and_b32_e32 v77, 0xffff0000, v77
	v_mul_f32_e32 v71, v75, v75
	v_mul_f32_e32 v72, v77, v77
	v_fmac_f32_e32 v71, v74, v74
	v_fmac_f32_e32 v72, v76, v76
	v_add_f32_e32 v71, v71, v72
	v_lshlrev_b32_e32 v72, 16, v142
	v_and_b32_e32 v73, 0xffff0000, v142
	v_pk_add_f32 v[62:63], v[62:63], v[72:73]
	v_lshlrev_b32_e32 v72, 16, v143
	v_and_b32_e32 v73, 0xffff0000, v143
	v_pk_add_f32 v[64:65], v[64:65], v[72:73]
	v_cvt_pk_bf16_f32 v62, v62, v63
	v_cvt_pk_bf16_f32 v63, v64, v65
	v_lshlrev_b32_e32 v64, 16, v144
	v_and_b32_e32 v65, 0xffff0000, v144
	v_pk_add_f32 v[58:59], v[58:59], v[64:65]
	v_add_f32_e32 v70, v70, v71
	v_cvt_pk_bf16_f32 v64, v58, v59
	v_lshlrev_b32_e32 v58, 16, v145
	v_and_b32_e32 v59, 0xffff0000, v145
	v_pk_add_f32 v[58:59], v[60:61], v[58:59]
	v_add_f32_e32 v74, v88, v70
	v_cvt_pk_bf16_f32 v65, v58, v59
	v_and_b32_e32 v59, 0xffff0000, v62
	v_lshl_add_u64 v[70:71], s[86:87], 0, v[224:225]
	v_lshlrev_b32_e32 v58, 16, v62
	v_and_b32_e32 v61, 0xffff0000, v63
	v_mul_f32_e32 v59, v59, v59
	v_lshl_add_u64 v[70:71], v[70:71], 0, v[216:217]
	v_lshlrev_b32_e32 v60, 16, v63
	v_fmac_f32_e32 v59, v58, v58
	v_mul_f32_e32 v58, v61, v61
	global_store_dwordx4 v[70:71], v[62:65], off
	v_fmac_f32_e32 v58, v60, v60
	v_add_f32_e32 v58, v59, v58
	v_lshlrev_b32_e32 v62, 16, v64
	v_and_b32_e32 v63, 0xffff0000, v64
	v_lshlrev_b32_e32 v64, 16, v65
	v_and_b32_e32 v65, 0xffff0000, v65
	v_mul_f32_e32 v59, v63, v63
	v_mul_f32_e32 v60, v65, v65
	v_fmac_f32_e32 v59, v62, v62
	v_fmac_f32_e32 v60, v64, v64
	v_add_f32_e32 v59, v59, v60
	v_add_f32_e32 v60, v58, v59
	v_lshlrev_b32_e32 v58, 16, v130
	v_and_b32_e32 v59, 0xffff0000, v130
	v_pk_add_f32 v[54:55], v[54:55], v[58:59]
	v_lshlrev_b32_e32 v58, 16, v131
	v_and_b32_e32 v59, 0xffff0000, v131
	v_pk_add_f32 v[56:57], v[56:57], v[58:59]
	v_cvt_pk_bf16_f32 v54, v54, v55
	v_cvt_pk_bf16_f32 v55, v56, v57
	v_lshlrev_b32_e32 v56, 16, v132
	v_and_b32_e32 v57, 0xffff0000, v132
	v_pk_add_f32 v[50:51], v[50:51], v[56:57]
	v_add_f32_e32 v146, v184, v146
	v_cvt_pk_bf16_f32 v56, v50, v51
	v_lshlrev_b32_e32 v50, 16, v133
	v_and_b32_e32 v51, 0xffff0000, v133
	v_pk_add_f32 v[50:51], v[52:53], v[50:51]
	v_and_b32_e32 v53, 0xffff0000, v55
	v_cvt_pk_bf16_f32 v57, v50, v51
	v_and_b32_e32 v51, 0xffff0000, v54
	v_lshlrev_b32_e32 v50, 16, v54
	v_mul_f32_e32 v51, v51, v51
	v_lshlrev_b32_e32 v52, 16, v55
	v_fmac_f32_e32 v51, v50, v50
	v_mul_f32_e32 v50, v53, v53
	global_store_dwordx4 v[70:71], v[54:57], off offset:256
	v_fmac_f32_e32 v50, v52, v52
	v_add_f32_e32 v50, v51, v50
	v_lshlrev_b32_e32 v54, 16, v56
	v_and_b32_e32 v55, 0xffff0000, v56
	v_lshlrev_b32_e32 v56, 16, v57
	v_and_b32_e32 v57, 0xffff0000, v57
	v_mul_f32_e32 v51, v55, v55
	v_mul_f32_e32 v52, v57, v57
	v_fmac_f32_e32 v51, v54, v54
	v_fmac_f32_e32 v52, v56, v56
	v_add_f32_e32 v51, v51, v52
	v_lshlrev_b32_e32 v52, 16, v118
	v_and_b32_e32 v53, 0xffff0000, v118
	v_pk_add_f32 v[46:47], v[46:47], v[52:53]
	v_lshlrev_b32_e32 v52, 16, v119
	v_and_b32_e32 v53, 0xffff0000, v119
	v_pk_add_f32 v[48:49], v[48:49], v[52:53]
	v_cvt_pk_bf16_f32 v46, v46, v47
	v_cvt_pk_bf16_f32 v47, v48, v49
	v_lshlrev_b32_e32 v48, 16, v120
	v_and_b32_e32 v49, 0xffff0000, v120
	v_pk_add_f32 v[42:43], v[42:43], v[48:49]
	v_add_f32_e32 v50, v50, v51
	v_cvt_pk_bf16_f32 v48, v42, v43
	v_lshlrev_b32_e32 v42, 16, v121
	v_and_b32_e32 v43, 0xffff0000, v121
	v_pk_add_f32 v[42:43], v[44:45], v[42:43]
	v_add_f32_e32 v54, v60, v50
	v_cvt_pk_bf16_f32 v49, v42, v43
	v_and_b32_e32 v43, 0xffff0000, v46
	v_lshl_add_u64 v[50:51], s[86:87], 0, v[222:223]
	v_lshlrev_b32_e32 v42, 16, v46
	v_and_b32_e32 v45, 0xffff0000, v47
	v_mul_f32_e32 v43, v43, v43
	v_lshl_add_u64 v[50:51], v[50:51], 0, v[216:217]
	v_lshlrev_b32_e32 v44, 16, v47
	v_fmac_f32_e32 v43, v42, v42
	v_mul_f32_e32 v42, v45, v45
	global_store_dwordx4 v[50:51], v[46:49], off
	v_fmac_f32_e32 v42, v44, v44
	v_add_f32_e32 v42, v43, v42
	v_lshlrev_b32_e32 v46, 16, v48
	v_and_b32_e32 v47, 0xffff0000, v48
	v_lshlrev_b32_e32 v48, 16, v49
	v_and_b32_e32 v49, 0xffff0000, v49
	v_mul_f32_e32 v43, v47, v47
	v_mul_f32_e32 v44, v49, v49
	v_fmac_f32_e32 v43, v46, v46
	v_fmac_f32_e32 v44, v48, v48
	v_add_f32_e32 v43, v43, v44
	v_add_f32_e32 v44, v42, v43
	v_lshlrev_b32_e32 v42, 16, v106
	v_and_b32_e32 v43, 0xffff0000, v106
	v_pk_add_f32 v[38:39], v[38:39], v[42:43]
	v_lshlrev_b32_e32 v42, 16, v107
	v_and_b32_e32 v43, 0xffff0000, v107
	v_pk_add_f32 v[40:41], v[40:41], v[42:43]
	v_cvt_pk_bf16_f32 v38, v38, v39
	v_cvt_pk_bf16_f32 v39, v40, v41
	v_lshlrev_b32_e32 v40, 16, v108
	v_and_b32_e32 v41, 0xffff0000, v108
	v_pk_add_f32 v[34:35], v[34:35], v[40:41]
	v_add_f32_e32 v122, v136, v122
	v_cvt_pk_bf16_f32 v40, v34, v35
	v_lshlrev_b32_e32 v34, 16, v109
	v_and_b32_e32 v35, 0xffff0000, v109
	v_pk_add_f32 v[34:35], v[36:37], v[34:35]
	v_and_b32_e32 v37, 0xffff0000, v39
	v_cvt_pk_bf16_f32 v41, v34, v35
	v_and_b32_e32 v35, 0xffff0000, v38
	v_lshlrev_b32_e32 v34, 16, v38
	v_mul_f32_e32 v35, v35, v35
	v_lshlrev_b32_e32 v36, 16, v39
	v_fmac_f32_e32 v35, v34, v34
	v_mul_f32_e32 v34, v37, v37
	global_store_dwordx4 v[50:51], v[38:41], off offset:256
	v_fmac_f32_e32 v34, v36, v36
	v_add_f32_e32 v34, v35, v34
	v_lshlrev_b32_e32 v38, 16, v40
	v_and_b32_e32 v39, 0xffff0000, v40
	v_lshlrev_b32_e32 v40, 16, v41
	v_and_b32_e32 v41, 0xffff0000, v41
	v_mul_f32_e32 v35, v39, v39
	v_mul_f32_e32 v36, v41, v41
	v_fmac_f32_e32 v35, v38, v38
	v_fmac_f32_e32 v36, v40, v40
	v_add_f32_e32 v35, v35, v36
	v_lshlrev_b32_e32 v36, 16, v98
	v_and_b32_e32 v37, 0xffff0000, v98
	v_pk_add_f32 v[30:31], v[30:31], v[36:37]
	v_lshlrev_b32_e32 v36, 16, v99
	v_and_b32_e32 v37, 0xffff0000, v99
	v_pk_add_f32 v[32:33], v[32:33], v[36:37]
	v_cvt_pk_bf16_f32 v30, v30, v31
	v_cvt_pk_bf16_f32 v31, v32, v33
	v_lshlrev_b32_e32 v32, 16, v100
	v_and_b32_e32 v33, 0xffff0000, v100
	v_pk_add_f32 v[26:27], v[26:27], v[32:33]
	v_add_f32_e32 v34, v34, v35
	v_cvt_pk_bf16_f32 v32, v26, v27
	v_lshlrev_b32_e32 v26, 16, v101
	v_and_b32_e32 v27, 0xffff0000, v101
	v_pk_add_f32 v[26:27], v[28:29], v[26:27]
	v_add_f32_e32 v38, v44, v34
	v_cvt_pk_bf16_f32 v33, v26, v27
	v_and_b32_e32 v27, 0xffff0000, v30
	v_lshl_add_u64 v[34:35], s[86:87], 0, v[220:221]
	v_lshlrev_b32_e32 v26, 16, v30
	v_and_b32_e32 v29, 0xffff0000, v31
	v_mul_f32_e32 v27, v27, v27
	v_lshl_add_u64 v[34:35], v[34:35], 0, v[216:217]
	v_lshlrev_b32_e32 v28, 16, v31
	v_fmac_f32_e32 v27, v26, v26
	v_mul_f32_e32 v26, v29, v29
	global_store_dwordx4 v[34:35], v[30:33], off
	v_fmac_f32_e32 v26, v28, v28
	v_add_f32_e32 v26, v27, v26
	v_lshlrev_b32_e32 v30, 16, v32
	v_and_b32_e32 v31, 0xffff0000, v32
	v_lshlrev_b32_e32 v32, 16, v33
	v_and_b32_e32 v33, 0xffff0000, v33
	v_mul_f32_e32 v27, v31, v31
	v_mul_f32_e32 v28, v33, v33
	v_fmac_f32_e32 v27, v30, v30
	v_fmac_f32_e32 v28, v32, v32
	v_add_f32_e32 v27, v27, v28
	v_add_f32_e32 v28, v26, v27
	v_lshlrev_b32_e32 v26, 16, v82
	v_and_b32_e32 v27, 0xffff0000, v82
	v_pk_add_f32 v[22:23], v[22:23], v[26:27]
	v_lshlrev_b32_e32 v26, 16, v83
	v_and_b32_e32 v27, 0xffff0000, v83
	v_pk_add_f32 v[24:25], v[24:25], v[26:27]
	v_cvt_pk_bf16_f32 v22, v22, v23
	v_cvt_pk_bf16_f32 v23, v24, v25
	v_lshlrev_b32_e32 v24, 16, v84
	v_and_b32_e32 v25, 0xffff0000, v84
	v_pk_add_f32 v[18:19], v[18:19], v[24:25]
	v_add_f32_e32 v94, v112, v94
	v_cvt_pk_bf16_f32 v24, v18, v19
	v_lshlrev_b32_e32 v18, 16, v85
	v_and_b32_e32 v19, 0xffff0000, v85
	v_pk_add_f32 v[18:19], v[20:21], v[18:19]
	v_and_b32_e32 v21, 0xffff0000, v23
	v_cvt_pk_bf16_f32 v25, v18, v19
	v_and_b32_e32 v19, 0xffff0000, v22
	v_lshlrev_b32_e32 v18, 16, v22
	v_mul_f32_e32 v19, v19, v19
	v_lshlrev_b32_e32 v20, 16, v23
	v_fmac_f32_e32 v19, v18, v18
	v_mul_f32_e32 v18, v21, v21
	global_store_dwordx4 v[34:35], v[22:25], off offset:256
	v_fmac_f32_e32 v18, v20, v20
	v_add_f32_e32 v18, v19, v18
	v_lshlrev_b32_e32 v22, 16, v24
	v_and_b32_e32 v23, 0xffff0000, v24
	v_lshlrev_b32_e32 v24, 16, v25
	v_and_b32_e32 v25, 0xffff0000, v25
	v_mul_f32_e32 v19, v23, v23
	v_mul_f32_e32 v20, v25, v25
	v_fmac_f32_e32 v19, v22, v22
	v_fmac_f32_e32 v20, v24, v24
	v_add_f32_e32 v19, v19, v20
	v_lshlrev_b32_e32 v20, 16, v78
	v_and_b32_e32 v21, 0xffff0000, v78
	v_pk_add_f32 v[14:15], v[14:15], v[20:21]
	v_lshlrev_b32_e32 v20, 16, v79
	v_and_b32_e32 v21, 0xffff0000, v79
	v_pk_add_f32 v[16:17], v[16:17], v[20:21]
	v_cvt_pk_bf16_f32 v14, v14, v15
	v_cvt_pk_bf16_f32 v15, v16, v17
	v_lshlrev_b32_e32 v16, 16, v80
	v_and_b32_e32 v17, 0xffff0000, v80
	v_pk_add_f32 v[10:11], v[10:11], v[16:17]
	v_add_f32_e32 v18, v18, v19
	v_cvt_pk_bf16_f32 v16, v10, v11
	v_lshlrev_b32_e32 v10, 16, v81
	v_and_b32_e32 v11, 0xffff0000, v81
	v_pk_add_f32 v[10:11], v[12:13], v[10:11]
	v_add_f32_e32 v22, v28, v18
	v_cvt_pk_bf16_f32 v17, v10, v11
	v_and_b32_e32 v11, 0xffff0000, v14
	v_lshl_add_u64 v[18:19], s[86:87], 0, v[218:219]
	v_lshlrev_b32_e32 v10, 16, v14
	v_and_b32_e32 v13, 0xffff0000, v15
	v_mul_f32_e32 v11, v11, v11
	v_lshl_add_u64 v[18:19], v[18:19], 0, v[216:217]
	v_lshlrev_b32_e32 v12, 16, v15
	v_fmac_f32_e32 v11, v10, v10
	v_mul_f32_e32 v10, v13, v13
	global_store_dwordx4 v[18:19], v[14:17], off
	v_fmac_f32_e32 v10, v12, v12
	v_add_f32_e32 v10, v11, v10
	v_lshlrev_b32_e32 v14, 16, v16
	v_and_b32_e32 v15, 0xffff0000, v16
	v_lshlrev_b32_e32 v16, 16, v17
	v_and_b32_e32 v17, 0xffff0000, v17
	v_mul_f32_e32 v11, v15, v15
	v_mul_f32_e32 v12, v17, v17
	v_fmac_f32_e32 v11, v14, v14
	v_fmac_f32_e32 v12, v16, v16
	v_add_f32_e32 v11, v11, v12
	v_add_f32_e32 v12, v10, v11
	v_lshlrev_b32_e32 v10, 16, v66
	v_and_b32_e32 v11, 0xffff0000, v66
	v_pk_add_f32 v[6:7], v[6:7], v[10:11]
	v_lshlrev_b32_e32 v10, 16, v67
	v_and_b32_e32 v11, 0xffff0000, v67
	v_pk_add_f32 v[8:9], v[8:9], v[10:11]
	v_cvt_pk_bf16_f32 v6, v6, v7
	v_cvt_pk_bf16_f32 v7, v8, v9
	v_lshlrev_b32_e32 v8, 16, v68
	v_and_b32_e32 v9, 0xffff0000, v68
	v_pk_add_f32 v[2:3], v[2:3], v[8:9]
	s_nop 0
	v_cvt_pk_bf16_f32 v8, v2, v3
	v_lshlrev_b32_e32 v2, 16, v69
	v_and_b32_e32 v3, 0xffff0000, v69
	v_pk_add_f32 v[2:3], v[4:5], v[2:3]
	v_and_b32_e32 v5, 0xffff0000, v7
	v_cvt_pk_bf16_f32 v9, v2, v3
	v_and_b32_e32 v3, 0xffff0000, v6
	v_lshlrev_b32_e32 v2, 16, v6
	v_mul_f32_e32 v3, v3, v3
	v_lshlrev_b32_e32 v4, 16, v7
	v_fmac_f32_e32 v3, v2, v2
	v_mul_f32_e32 v2, v5, v5
	global_store_dwordx4 v[18:19], v[6:9], off offset:256
	v_fmac_f32_e32 v2, v4, v4
	v_add_f32_e32 v2, v3, v2
	v_lshlrev_b32_e32 v6, 16, v8
	v_and_b32_e32 v7, 0xffff0000, v8
	v_lshlrev_b32_e32 v8, 16, v9
	v_and_b32_e32 v9, 0xffff0000, v9
	v_mul_f32_e32 v3, v7, v7
	v_mul_f32_e32 v4, v9, v9
	v_fmac_f32_e32 v3, v6, v6
	v_fmac_f32_e32 v4, v8, v8
	v_add_f32_e32 v3, v3, v4
	v_add_f32_e32 v2, v2, v3
	v_add_f32_e32 v8, v12, v2
	v_mov_b32_e32 v2, v0
	s_nop 0
	v_lshlrev_b32_e32 v10, 2, v2
	v_bitop3_b32 v2, v10, 64, v196 bitop3:0x6c
	ds_bpermute_b32 v3, v2, v146
	ds_bpermute_b32 v4, v2, v122
	ds_bpermute_b32 v5, v2, v94
	ds_bpermute_b32 v6, v2, v74
	ds_bpermute_b32 v7, v2, v54
	ds_bpermute_b32 v9, v2, v38
	ds_bpermute_b32 v11, v2, v22
	ds_bpermute_b32 v12, v2, v8
	s_waitcnt lgkmcnt(7)
	v_add_f32_e32 v2, v146, v3
	s_waitcnt lgkmcnt(6)
	v_add_f32_e32 v3, v122, v4
	s_waitcnt lgkmcnt(5)
	v_add_f32_e32 v4, v94, v5
	s_waitcnt lgkmcnt(4)
	v_add_f32_e32 v5, v74, v6
	s_waitcnt lgkmcnt(3)
	v_add_f32_e32 v6, v54, v7
	s_waitcnt lgkmcnt(2)
	v_add_f32_e32 v7, v38, v9
	s_waitcnt lgkmcnt(1)
	v_add_f32_e32 v9, v22, v11
	s_waitcnt lgkmcnt(0)
	v_add_f32_e32 v11, v8, v12
	v_bitop3_b32 v17, v10, s18, v196 bitop3:0x6c
	ds_bpermute_b32 v8, v17, v2
	ds_bpermute_b32 v10, v17, v3
	ds_bpermute_b32 v12, v17, v4
	ds_bpermute_b32 v13, v17, v5
	ds_bpermute_b32 v14, v17, v6
	ds_bpermute_b32 v15, v17, v7
	ds_bpermute_b32 v16, v17, v9
	ds_bpermute_b32 v17, v17, v11
	s_and_saveexec_b64 s[18:19], s[2:3]
	s_cbranch_execz .LBB0_855
	s_waitcnt lgkmcnt(5)
	v_add_f32_e32 v12, v4, v12
	v_add_f32_e32 v4, v2, v8
	s_mov_b32 s20, 0x49800000
	v_fma_f32 v4, v4, s20, 0.5
	v_trunc_f32_e32 v4, v4
	s_waitcnt lgkmcnt(4)
	v_add_f32_e32 v13, v5, v13
	v_mul_f32_e32 v5, 0x2f800000, v4
	v_floor_f32_e32 v5, v5
	v_fmac_f32_e32 v4, 0xcf800000, v5
	v_cvt_u32_f32_e32 v4, v4
	v_cvt_u32_f32_e32 v5, v5
	v_add_f32_e32 v10, v3, v10
	v_lshl_add_u64 v[2:3], v[214:215], 3, s[80:81]
	s_waitcnt lgkmcnt(3)
	v_add_f32_e32 v6, v6, v14
	global_atomic_add_x2 v[2:3], v[4:5], off
	v_fma_f32 v4, v10, s20, 0.5
	v_trunc_f32_e32 v4, v4
	v_mul_f32_e32 v5, 0x2f800000, v4
	v_floor_f32_e32 v5, v5
	v_fmac_f32_e32 v4, 0xcf800000, v5
	v_cvt_u32_f32_e32 v4, v4
	v_cvt_u32_f32_e32 v5, v5
	s_waitcnt lgkmcnt(2)
	v_add_f32_e32 v7, v7, v15
	s_waitcnt lgkmcnt(1)
	v_add_f32_e32 v9, v9, v16
	s_waitcnt lgkmcnt(0)
	v_add_f32_e32 v11, v11, v17
	global_atomic_add_x2 v[2:3], v[4:5], off offset:128
	v_fma_f32 v4, v12, s20, 0.5
	v_trunc_f32_e32 v4, v4
	v_mul_f32_e32 v5, 0x2f800000, v4
	v_floor_f32_e32 v5, v5
	v_fmac_f32_e32 v4, 0xcf800000, v5
	v_cvt_u32_f32_e32 v4, v4
	v_cvt_u32_f32_e32 v5, v5
	global_atomic_add_x2 v[2:3], v[4:5], off offset:256
	v_fma_f32 v4, v13, s20, 0.5
	v_trunc_f32_e32 v4, v4
	v_mul_f32_e32 v5, 0x2f800000, v4
	v_floor_f32_e32 v5, v5
	v_fmac_f32_e32 v4, 0xcf800000, v5
	v_cvt_u32_f32_e32 v4, v4
	v_cvt_u32_f32_e32 v5, v5
	global_atomic_add_x2 v[2:3], v[4:5], off offset:384
	v_fma_f32 v4, v6, s20, 0.5
	v_trunc_f32_e32 v4, v4
	v_mul_f32_e32 v5, 0x2f800000, v4
	v_floor_f32_e32 v5, v5
	v_fmac_f32_e32 v4, 0xcf800000, v5
	v_cvt_u32_f32_e32 v4, v4
	v_cvt_u32_f32_e32 v5, v5
	global_atomic_add_x2 v[2:3], v[4:5], off offset:1024
	v_fma_f32 v4, v7, s20, 0.5
	v_trunc_f32_e32 v4, v4
	v_mul_f32_e32 v5, 0x2f800000, v4
	v_floor_f32_e32 v5, v5
	v_fmac_f32_e32 v4, 0xcf800000, v5
	v_cvt_u32_f32_e32 v4, v4
	v_cvt_u32_f32_e32 v5, v5
	global_atomic_add_x2 v[2:3], v[4:5], off offset:1152
	v_fma_f32 v4, v9, s20, 0.5
	v_trunc_f32_e32 v4, v4
	v_mul_f32_e32 v5, 0x2f800000, v4
	v_floor_f32_e32 v5, v5
	v_fmac_f32_e32 v4, 0xcf800000, v5
	v_cvt_u32_f32_e32 v4, v4
	v_cvt_u32_f32_e32 v5, v5
	global_atomic_add_x2 v[2:3], v[4:5], off offset:1280
	v_fma_f32 v4, v11, s20, 0.5
	v_trunc_f32_e32 v4, v4
	v_mul_f32_e32 v5, 0x2f800000, v4
	v_floor_f32_e32 v5, v5
	v_fmac_f32_e32 v4, 0xcf800000, v5
	v_cvt_u32_f32_e32 v4, v4
	v_cvt_u32_f32_e32 v5, v5
	global_atomic_add_x2 v[2:3], v[4:5], off offset:1408

.LBB0_973:
	s_add_u32 vcc_lo, s0, 0xffffc000
	s_addc_u32 vcc_hi, s1, -1
	s_mov_b32 m0, s59
	s_nop 0
	global_load_lds_dwordx4 v146, vcc
	s_mov_b32 m0, s60
	s_nop 0
	global_load_lds_dwordx4 v148, vcc
	ds_read_b128 v[130:133], v246
	ds_read_b128 v[134:137], v246 offset:1024
	ds_read_b128 v[150:153], v246 offset:2048
	ds_read_b128 v[154:157], v246 offset:3072
	ds_read_b128 v[158:161], v246 offset:16384
	ds_read_b128 v[162:165], v246 offset:17408
	ds_read_b128 v[166:169], v246 offset:18432
	ds_read_b128 v[170:173], v246 offset:19456
	ds_read_b128 v[174:177], v247
	ds_read_b128 v[178:181], v247 offset:1024
	ds_read_b128 v[182:185], v247 offset:2048
	ds_read_b128 v[186:189], v247 offset:3072
	ds_read_b128 v[190:193], v247 offset:4096
	ds_read_b128 v[204:207], v247 offset:5120
	ds_read_b128 v[208:211], v247 offset:6144
	ds_read_b128 v[212:215], v247 offset:7168
	s_add_u32 s4, s0, 0x100
	s_addc_u32 s5, s1, 0
	s_add_i32 s40, 0, 0x10000
	s_cmp_eq_u32 s39, 28
	s_cselect_b32 s11, s35, s5
	s_cselect_b32 s10, s34, s4
	s_cselect_b32 s7, s13, s38
	s_cselect_b32 s6, s29, s33
	s_add_i32 s41, 0, 0x14000
	s_add_i32 m0, s49, 0xc000
	s_nop 0
	global_load_lds_dwordx4 v146, s[0:1]
	s_add_i32 m0, s49, 0xe000
	s_nop 0
	global_load_lds_dwordx4 v148, s[0:1]
	s_waitcnt vmcnt(8)
	s_waitcnt lgkmcnt(0)
	v_mfma_f32_16x16x32_bf16 v[126:129], v[130:133], v[174:177], v[126:129]
	v_mfma_f32_16x16x32_bf16 v[126:129], v[134:137], v[178:181], v[126:129]
	s_barrier
	s_setprio 1
	v_mfma_f32_16x16x32_bf16 v[62:65], v[154:157], v[178:181], v[62:65]
	v_mfma_f32_16x16x32_bf16 v[62:65], v[150:153], v[174:177], v[62:65]
	v_mfma_f32_16x16x32_bf16 v[58:61], v[150:153], v[182:185], v[58:61]
	v_mfma_f32_16x16x32_bf16 v[58:61], v[154:157], v[186:189], v[58:61]
	v_mfma_f32_16x16x32_bf16 v[122:125], v[134:137], v[186:189], v[122:125]
	v_mfma_f32_16x16x32_bf16 v[122:125], v[130:133], v[182:185], v[122:125]
	v_mfma_f32_16x16x32_bf16 v[114:117], v[130:133], v[190:193], v[114:117]
	v_mfma_f32_16x16x32_bf16 v[114:117], v[134:137], v[204:207], v[114:117]
	v_mfma_f32_16x16x32_bf16 v[50:53], v[154:157], v[204:207], v[50:53]
	v_mfma_f32_16x16x32_bf16 v[50:53], v[150:153], v[190:193], v[50:53]
	v_mfma_f32_16x16x32_bf16 v[42:45], v[150:153], v[208:211], v[42:45]
	v_mfma_f32_16x16x32_bf16 v[42:45], v[154:157], v[212:215], v[42:45]
	v_mfma_f32_16x16x32_bf16 v[106:109], v[134:137], v[212:215], v[106:109]
	v_mfma_f32_16x16x32_bf16 v[106:109], v[130:133], v[208:211], v[106:109]
	v_mfma_f32_16x16x32_bf16 v[118:121], v[158:161], v[174:177], v[118:121]
	v_mfma_f32_16x16x32_bf16 v[118:121], v[162:165], v[178:181], v[118:121]
	v_mfma_f32_16x16x32_bf16 v[54:57], v[170:173], v[178:181], v[54:57]
	v_mfma_f32_16x16x32_bf16 v[54:57], v[166:169], v[174:177], v[54:57]
	v_mfma_f32_16x16x32_bf16 v[46:49], v[166:169], v[182:185], v[46:49]
	v_mfma_f32_16x16x32_bf16 v[46:49], v[170:173], v[186:189], v[46:49]
	v_mfma_f32_16x16x32_bf16 v[110:113], v[162:165], v[186:189], v[110:113]
	v_mfma_f32_16x16x32_bf16 v[110:113], v[158:161], v[182:185], v[110:113]
	v_mfma_f32_16x16x32_bf16 v[102:105], v[158:161], v[190:193], v[102:105]
	v_mfma_f32_16x16x32_bf16 v[102:105], v[162:165], v[204:207], v[102:105]
	v_mfma_f32_16x16x32_bf16 v[38:41], v[170:173], v[204:207], v[38:41]
	v_mfma_f32_16x16x32_bf16 v[38:41], v[166:169], v[190:193], v[38:41]
	v_mfma_f32_16x16x32_bf16 v[34:37], v[166:169], v[208:211], v[34:37]
	v_mfma_f32_16x16x32_bf16 v[34:37], v[170:173], v[212:215], v[34:37]
	v_mfma_f32_16x16x32_bf16 v[98:101], v[162:165], v[212:215], v[98:101]
	v_mfma_f32_16x16x32_bf16 v[98:101], v[158:161], v[208:211], v[98:101]
	s_setprio 0
	s_barrier
	ds_read_b128 v[174:177], v247 offset:16384
	ds_read_b128 v[178:181], v247 offset:17408
	ds_read_b128 v[182:185], v247 offset:18432
	ds_read_b128 v[186:189], v247 offset:19456
	ds_read_b128 v[190:193], v247 offset:20480
	ds_read_b128 v[204:207], v247 offset:21504
	ds_read_b128 v[208:211], v247 offset:22528
	ds_read_b128 v[212:215], v247 offset:23552
	s_add_i32 s0, s40, s48
	s_mov_b32 m0, s0
	s_nop 0
	global_load_lds_dwordx4 v140, s[6:7]
	s_add_i32 m0, s0, 0x2000
	s_add_u32 s0, s6, 0x80000
	s_addc_u32 s1, s7, 0
	s_add_i32 s40, s41, s48
	global_load_lds_dwordx4 v144, s[6:7]
	s_mov_b32 m0, s40
	s_nop 0
	global_load_lds_dwordx4 v140, s[0:1]
	s_add_i32 m0, s40, 0x2000
	s_nop 0
	global_load_lds_dwordx4 v144, s[0:1]
	s_waitcnt vmcnt(6)
	s_waitcnt lgkmcnt(0)
	v_mfma_f32_16x16x32_bf16 v[94:97], v[130:133], v[174:177], v[94:97]
	v_mfma_f32_16x16x32_bf16 v[94:97], v[134:137], v[178:181], v[94:97]
	s_barrier
	s_setprio 1
	v_mfma_f32_16x16x32_bf16 v[30:33], v[154:157], v[178:181], v[30:33]
	v_mfma_f32_16x16x32_bf16 v[30:33], v[150:153], v[174:177], v[30:33]
	v_mfma_f32_16x16x32_bf16 v[26:29], v[150:153], v[182:185], v[26:29]
	v_mfma_f32_16x16x32_bf16 v[26:29], v[154:157], v[186:189], v[26:29]
	v_mfma_f32_16x16x32_bf16 v[90:93], v[134:137], v[186:189], v[90:93]
	v_mfma_f32_16x16x32_bf16 v[90:93], v[130:133], v[182:185], v[90:93]
	v_mfma_f32_16x16x32_bf16 v[82:85], v[130:133], v[190:193], v[82:85]
	v_mfma_f32_16x16x32_bf16 v[82:85], v[134:137], v[204:207], v[82:85]
	v_mfma_f32_16x16x32_bf16 v[18:21], v[154:157], v[204:207], v[18:21]
	v_mfma_f32_16x16x32_bf16 v[18:21], v[150:153], v[190:193], v[18:21]
	v_mfma_f32_16x16x32_bf16 v[10:13], v[150:153], v[208:211], v[10:13]
	v_mfma_f32_16x16x32_bf16 v[10:13], v[154:157], v[212:215], v[10:13]
	v_mfma_f32_16x16x32_bf16 v[74:77], v[134:137], v[212:215], v[74:77]
	v_mfma_f32_16x16x32_bf16 v[74:77], v[130:133], v[208:211], v[74:77]
	v_mfma_f32_16x16x32_bf16 v[86:89], v[158:161], v[174:177], v[86:89]
	v_mfma_f32_16x16x32_bf16 v[86:89], v[162:165], v[178:181], v[86:89]
	v_mfma_f32_16x16x32_bf16 v[22:25], v[170:173], v[178:181], v[22:25]
	v_mfma_f32_16x16x32_bf16 v[22:25], v[166:169], v[174:177], v[22:25]
	v_mfma_f32_16x16x32_bf16 v[14:17], v[166:169], v[182:185], v[14:17]
	v_mfma_f32_16x16x32_bf16 v[14:17], v[170:173], v[186:189], v[14:17]
	v_mfma_f32_16x16x32_bf16 v[78:81], v[162:165], v[186:189], v[78:81]
	v_mfma_f32_16x16x32_bf16 v[78:81], v[158:161], v[182:185], v[78:81]
	v_mfma_f32_16x16x32_bf16 v[70:73], v[158:161], v[190:193], v[70:73]
	v_mfma_f32_16x16x32_bf16 v[70:73], v[162:165], v[204:207], v[70:73]
	v_mfma_f32_16x16x32_bf16 v[6:9], v[170:173], v[204:207], v[6:9]
	v_mfma_f32_16x16x32_bf16 v[6:9], v[166:169], v[190:193], v[6:9]
	v_mfma_f32_16x16x32_bf16 v[2:5], v[166:169], v[208:211], v[2:5]
	v_mfma_f32_16x16x32_bf16 v[2:5], v[170:173], v[212:215], v[2:5]
	v_mfma_f32_16x16x32_bf16 v[66:69], v[162:165], v[212:215], v[66:69]
	v_mfma_f32_16x16x32_bf16 v[66:69], v[158:161], v[208:211], v[66:69]
	s_setprio 0
	s_barrier
	s_mov_b32 m0, s49
	s_nop 0
	global_load_lds_dwordx4 v138, s[10:11]
	s_mov_b32 m0, s70
	s_nop 0
	global_load_lds_dwordx4 v142, s[10:11]
	ds_read_b128 v[130:133], v246 offset:32768
	ds_read_b128 v[134:137], v246 offset:33792
	ds_read_b128 v[150:153], v246 offset:34816
	ds_read_b128 v[154:157], v246 offset:35840
	ds_read_b128 v[158:161], v246 offset:49152
	ds_read_b128 v[162:165], v246 offset:50176
	ds_read_b128 v[166:169], v246 offset:51200
	ds_read_b128 v[170:173], v246 offset:52224
	ds_read_b128 v[174:177], v247 offset:32768
	ds_read_b128 v[178:181], v247 offset:33792
	ds_read_b128 v[182:185], v247 offset:34816
	ds_read_b128 v[186:189], v247 offset:35840
	ds_read_b128 v[190:193], v247 offset:36864
	ds_read_b128 v[204:207], v247 offset:37888
	ds_read_b128 v[208:211], v247 offset:38912
	ds_read_b128 v[212:215], v247 offset:39936
	s_add_i32 s40, 0, 0x18000
	s_add_i32 s41, 0, 0x1c000
	s_add_u32 s0, s10, 0x4000
	s_addc_u32 s1, s11, 0
	s_mov_b32 m0, s71
	s_nop 0
	global_load_lds_dwordx4 v138, s[0:1]
	s_mov_b32 m0, s73
	s_nop 0
	global_load_lds_dwordx4 v142, s[0:1]
	s_waitcnt vmcnt(8)
	s_waitcnt lgkmcnt(0)
	v_mfma_f32_16x16x32_bf16 v[126:129], v[130:133], v[174:177], v[126:129]
	v_mfma_f32_16x16x32_bf16 v[126:129], v[134:137], v[178:181], v[126:129]
	s_barrier
	s_setprio 1
	v_mfma_f32_16x16x32_bf16 v[62:65], v[154:157], v[178:181], v[62:65]
	v_mfma_f32_16x16x32_bf16 v[62:65], v[150:153], v[174:177], v[62:65]
	v_mfma_f32_16x16x32_bf16 v[58:61], v[150:153], v[182:185], v[58:61]
	v_mfma_f32_16x16x32_bf16 v[58:61], v[154:157], v[186:189], v[58:61]
	v_mfma_f32_16x16x32_bf16 v[122:125], v[134:137], v[186:189], v[122:125]
	v_mfma_f32_16x16x32_bf16 v[122:125], v[130:133], v[182:185], v[122:125]
	v_mfma_f32_16x16x32_bf16 v[114:117], v[130:133], v[190:193], v[114:117]
	v_mfma_f32_16x16x32_bf16 v[114:117], v[134:137], v[204:207], v[114:117]
	v_mfma_f32_16x16x32_bf16 v[50:53], v[154:157], v[204:207], v[50:53]
	v_mfma_f32_16x16x32_bf16 v[50:53], v[150:153], v[190:193], v[50:53]
	v_mfma_f32_16x16x32_bf16 v[42:45], v[150:153], v[208:211], v[42:45]
	v_mfma_f32_16x16x32_bf16 v[42:45], v[154:157], v[212:215], v[42:45]
	v_mfma_f32_16x16x32_bf16 v[106:109], v[134:137], v[212:215], v[106:109]
	v_mfma_f32_16x16x32_bf16 v[106:109], v[130:133], v[208:211], v[106:109]
	v_mfma_f32_16x16x32_bf16 v[118:121], v[158:161], v[174:177], v[118:121]
	v_mfma_f32_16x16x32_bf16 v[118:121], v[162:165], v[178:181], v[118:121]
	v_mfma_f32_16x16x32_bf16 v[54:57], v[170:173], v[178:181], v[54:57]
	v_mfma_f32_16x16x32_bf16 v[54:57], v[166:169], v[174:177], v[54:57]
	v_mfma_f32_16x16x32_bf16 v[46:49], v[166:169], v[182:185], v[46:49]
	v_mfma_f32_16x16x32_bf16 v[46:49], v[170:173], v[186:189], v[46:49]
	v_mfma_f32_16x16x32_bf16 v[110:113], v[162:165], v[186:189], v[110:113]
	v_mfma_f32_16x16x32_bf16 v[110:113], v[158:161], v[182:185], v[110:113]
	v_mfma_f32_16x16x32_bf16 v[102:105], v[158:161], v[190:193], v[102:105]
	v_mfma_f32_16x16x32_bf16 v[102:105], v[162:165], v[204:207], v[102:105]
	v_mfma_f32_16x16x32_bf16 v[38:41], v[170:173], v[204:207], v[38:41]
	v_mfma_f32_16x16x32_bf16 v[38:41], v[166:169], v[190:193], v[38:41]
	v_mfma_f32_16x16x32_bf16 v[34:37], v[166:169], v[208:211], v[34:37]
	v_mfma_f32_16x16x32_bf16 v[34:37], v[170:173], v[212:215], v[34:37]
	v_mfma_f32_16x16x32_bf16 v[98:101], v[162:165], v[212:215], v[98:101]
	v_mfma_f32_16x16x32_bf16 v[98:101], v[158:161], v[208:211], v[98:101]
	s_setprio 0
	s_barrier
	ds_read_b128 v[174:177], v247 offset:49152
	ds_read_b128 v[178:181], v247 offset:50176
	ds_read_b128 v[182:185], v247 offset:51200
	ds_read_b128 v[186:189], v247 offset:52224
	ds_read_b128 v[190:193], v247 offset:53248
	ds_read_b128 v[204:207], v247 offset:54272
	ds_read_b128 v[208:211], v247 offset:55296
	ds_read_b128 v[212:215], v247 offset:56320
	s_add_i32 s0, s40, s48
	s_add_u32 vcc_lo, s6, s94
	s_addc_u32 vcc_hi, s7, s95
	s_mov_b32 m0, s0
	s_nop 0
	global_load_lds_dwordx4 v140, vcc
	s_add_i32 m0, s0, 0x2000
	s_add_u32 s0, s6, 0x80080
	s_addc_u32 s1, s7, 0
	s_add_i32 s6, s41, s48
	global_load_lds_dwordx4 v144, vcc
	s_mov_b32 m0, s6
	s_nop 0
	global_load_lds_dwordx4 v140, s[0:1]
	s_add_i32 m0, s6, 0x2000
	s_nop 0
	global_load_lds_dwordx4 v144, s[0:1]
	s_waitcnt vmcnt(6)
	s_waitcnt lgkmcnt(0)
	v_mfma_f32_16x16x32_bf16 v[94:97], v[130:133], v[174:177], v[94:97]
	v_mfma_f32_16x16x32_bf16 v[94:97], v[134:137], v[178:181], v[94:97]
	s_barrier
	s_setprio 1
	v_mfma_f32_16x16x32_bf16 v[30:33], v[154:157], v[178:181], v[30:33]
	v_mfma_f32_16x16x32_bf16 v[30:33], v[150:153], v[174:177], v[30:33]
	v_mfma_f32_16x16x32_bf16 v[26:29], v[150:153], v[182:185], v[26:29]
	v_mfma_f32_16x16x32_bf16 v[26:29], v[154:157], v[186:189], v[26:29]
	v_mfma_f32_16x16x32_bf16 v[90:93], v[134:137], v[186:189], v[90:93]
	v_mfma_f32_16x16x32_bf16 v[90:93], v[130:133], v[182:185], v[90:93]
	v_mfma_f32_16x16x32_bf16 v[82:85], v[130:133], v[190:193], v[82:85]
	v_mfma_f32_16x16x32_bf16 v[82:85], v[134:137], v[204:207], v[82:85]
	v_mfma_f32_16x16x32_bf16 v[18:21], v[154:157], v[204:207], v[18:21]
	v_mfma_f32_16x16x32_bf16 v[18:21], v[150:153], v[190:193], v[18:21]
	v_mfma_f32_16x16x32_bf16 v[10:13], v[150:153], v[208:211], v[10:13]
	v_mfma_f32_16x16x32_bf16 v[10:13], v[154:157], v[212:215], v[10:13]
	s_add_i32 s39, s39, 2
	v_mfma_f32_16x16x32_bf16 v[74:77], v[134:137], v[212:215], v[74:77]
	v_mfma_f32_16x16x32_bf16 v[74:77], v[130:133], v[208:211], v[74:77]
	s_add_u32 s33, s33, 0x100
	v_mfma_f32_16x16x32_bf16 v[86:89], v[158:161], v[174:177], v[86:89]
	v_mfma_f32_16x16x32_bf16 v[86:89], v[162:165], v[178:181], v[86:89]
	s_addc_u32 s38, s38, 0
	v_mfma_f32_16x16x32_bf16 v[22:25], v[170:173], v[178:181], v[22:25]
	v_mfma_f32_16x16x32_bf16 v[22:25], v[166:169], v[174:177], v[22:25]
	s_cmp_gt_u32 s39, 29
	v_mfma_f32_16x16x32_bf16 v[14:17], v[166:169], v[182:185], v[14:17]
	v_mfma_f32_16x16x32_bf16 v[14:17], v[170:173], v[186:189], v[14:17]
	s_mov_b64 s[0:1], s[4:5]
	v_mfma_f32_16x16x32_bf16 v[78:81], v[162:165], v[186:189], v[78:81]
	v_mfma_f32_16x16x32_bf16 v[78:81], v[158:161], v[182:185], v[78:81]
	v_mfma_f32_16x16x32_bf16 v[70:73], v[158:161], v[190:193], v[70:73]
	v_mfma_f32_16x16x32_bf16 v[70:73], v[162:165], v[204:207], v[70:73]
	v_mfma_f32_16x16x32_bf16 v[6:9], v[170:173], v[204:207], v[6:9]
	v_mfma_f32_16x16x32_bf16 v[6:9], v[166:169], v[190:193], v[6:9]
	v_mfma_f32_16x16x32_bf16 v[2:5], v[166:169], v[208:211], v[2:5]
	v_mfma_f32_16x16x32_bf16 v[2:5], v[170:173], v[212:215], v[2:5]
	v_mfma_f32_16x16x32_bf16 v[66:69], v[162:165], v[212:215], v[66:69]
	v_mfma_f32_16x16x32_bf16 v[66:69], v[158:161], v[208:211], v[66:69]
	s_setprio 0
	s_barrier
	s_cbranch_scc0 .LBB0_973
.LBB0_976:
	s_and_b64 vcc, exec, s[2:3]
	s_and_b32 s4, s9, 1
	s_cbranch_vccnz .LBB0_979
	v_mov_b32_e32 v131, v0
	s_mov_b32 s7, s28
	v_readfirstlane_b32 s5, v131
	v_and_b32_e32 v130, 63, v131
	s_ashr_i32 s1, s5, 8
	s_bfe_u32 s6, s5, 0x20006
	s_mov_b32 s5, s62
	v_cmp_gt_u32_e32 vcc, 32, v130
	v_mov_b32_e32 v132, 0x1600
	s_xor_b32 s0, s4, 1
	v_cndmask_b32_e64 v132, v132, 0, vcc
	v_and_b32_e32 v131, 31, v131
	v_lshl_add_u32 v132, s7, 7, v132
	s_lshl_b32 s7, s6, 5
	s_lshl_b32 s9, s1, 2
	v_or3_b32 v132, v132, s7, v131
	s_mul_i32 s7, s0, 0x3000
	s_or_b32 s9, s9, s6
	s_add_i32 s7, s7, 0
	s_mulk_i32 s9, 0x600
	v_ashrrev_i32_e32 v133, 31, v132
	s_add_i32 s7, s7, s9
	v_lshlrev_b64 v[132:133], 2, v[132:133]
	s_add_i32 m0, s7, 0x20000
	v_lshl_add_u64 v[134:135], s[14:15], 0, v[132:133]
	global_load_lds_dword v[134:135], off
	v_lshl_add_u64 v[134:135], s[18:19], 0, v[132:133]
	s_add_i32 m0, s7, 0x20100
	s_nop 0
	global_load_lds_dword v[134:135], off
	v_lshl_add_u64 v[134:135], s[20:21], 0, v[132:133]
	s_add_i32 m0, s7, 0x20200
	v_lshl_add_u64 v[132:133], s[16:17], 0, v[132:133]
	global_load_lds_dword v[134:135], off
	s_add_i32 m0, s7, 0x20300
	s_cmp_lg_u32 s6, 0
	global_load_lds_dword v[132:133], off
	s_cbranch_scc1 .LBB0_979
	s_mulk_i32 s5, 0xfc
	s_mul_i32 s6, s1, 0x7e
	s_add_i32 s5, s6, s5
	s_add_i32 s6, s5, -2
	s_ashr_i32 s7, s6, 31
	s_lshl_b64 s[6:7], s[6:7], 3
	s_add_u32 s6, s80, s6
	s_addc_u32 s7, s81, s7
	s_lshl_b32 s0, s0, 11
	s_add_i32 s0, s0, 0
	s_lshl_b32 s1, s1, 10
	s_add_i32 s0, s0, s1
	v_lshlrev_b32_e32 v194, 2, v130
	s_add_i32 m0, s0, 0x26000
	v_lshl_add_u64 v[130:131], s[6:7], 0, v[194:195]
	global_load_lds_dword v194, s[6:7]
	s_mov_b64 s[6:7], 0x100
	v_lshl_add_u64 v[132:133], v[130:131], 0, s[6:7]
	s_add_i32 m0, s0, 0x26100
	s_mov_b64 s[6:7], 0x200
	global_load_lds_dword v[132:133], off
	v_lshl_add_u64 v[132:133], v[130:131], 0, s[6:7]
	s_add_i32 m0, s0, 0x26200
	s_mov_b64 s[6:7], 0x300
	global_load_lds_dword v[132:133], off
	v_lshl_add_u64 v[130:131], v[130:131], 0, s[6:7]
	s_add_i32 m0, s0, 0x26300
	s_nop 0
	global_load_lds_dword v[130:131], off

.LBB0_981:
	s_bfe_u32 s12, s6, 0x20006
	s_mul_i32 s6, s4, 0x3000
	s_lshl_b32 s4, s4, 11
	s_add_i32 s4, s4, 0
	s_lshl_b32 s7, s5, 10
	v_and_b32_e32 v153, 15, v130
	v_lshrrev_b32_e32 v130, 1, v130
	s_add_i32 s4, s4, s7
	v_and_b32_e32 v151, 24, v130
	v_lshl_add_u32 v130, v153, 6, s4
	v_add_u32_e32 v150, 0x26000, v130
	ds_read_b128 v[130:133], v150
	ds_read_b128 v[134:137], v150 offset:16
	ds_read_b128 v[156:159], v150 offset:32
	ds_read_b128 v[160:163], v150 offset:48
	s_and_b64 vcc, exec, s[26:27]
	s_cbranch_vccz .Lalign_l7
	s_barrier
.Lalign_l7:
	s_lshl_b32 s4, s5, 2
	s_or_b32 s4, s4, s12
	s_waitcnt lgkmcnt(0)
	v_ffbh_u32_e32 v152, v131
	v_min_u32_e32 v152, 32, v152
	v_lshlrev_b64 v[130:131], v152, v[130:131]
	v_min_u32_e32 v130, 1, v130
	v_or_b32_e32 v130, v131, v130
	v_cvt_f32_u32_e32 v130, v130
	v_sub_u32_e32 v131, 32, v152
	s_mulk_i32 s4, 0x600
	s_add_i32 s5, s6, 0
	v_ldexp_f32 v150, v130, v131
	v_ffbh_u32_e32 v130, v133
	v_min_u32_e32 v152, 32, v130
	v_lshlrev_b64 v[130:131], v152, v[132:133]
	v_min_u32_e32 v130, 1, v130
	v_or_b32_e32 v130, v131, v130
	v_cvt_f32_u32_e32 v130, v130
	v_fmamk_f32 v131, v150, 0x30000000, v1
	v_rsq_f32_e32 v150, v131
	v_sub_u32_e32 v131, 32, v152
	v_ldexp_f32 v132, v130, v131
	v_ffbh_u32_e32 v130, v135
	v_min_u32_e32 v133, 32, v130
	v_lshlrev_b64 v[130:131], v133, v[134:135]
	v_min_u32_e32 v130, 1, v130
	v_or_b32_e32 v130, v131, v130
	v_cvt_f32_u32_e32 v130, v130
	v_fmamk_f32 v131, v132, 0x30000000, v1
	v_rsq_f32_e32 v152, v131
	v_sub_u32_e32 v131, 32, v133
	v_ldexp_f32 v132, v130, v131
	v_ffbh_u32_e32 v130, v137
	v_min_u32_e32 v133, 32, v130
	v_lshlrev_b64 v[130:131], v133, v[136:137]
	v_min_u32_e32 v130, 1, v130
	v_or_b32_e32 v130, v131, v130
	v_cvt_f32_u32_e32 v130, v130
	v_fmamk_f32 v131, v132, 0x30000000, v1
	v_rsq_f32_e32 v154, v131
	v_sub_u32_e32 v131, 32, v133
	v_ldexp_f32 v132, v130, v131
	v_ffbh_u32_e32 v130, v157
	v_min_u32_e32 v133, 32, v130
	v_lshlrev_b64 v[130:131], v133, v[156:157]
	v_min_u32_e32 v130, 1, v130
	v_or_b32_e32 v130, v131, v130
	v_cvt_f32_u32_e32 v130, v130
	v_fmamk_f32 v131, v132, 0x30000000, v1
	v_rsq_f32_e32 v156, v131
	v_sub_u32_e32 v131, 32, v133
	v_ldexp_f32 v132, v130, v131
	v_ffbh_u32_e32 v130, v159
	v_min_u32_e32 v133, 32, v130
	v_lshlrev_b64 v[130:131], v133, v[158:159]
	v_min_u32_e32 v130, 1, v130
	v_or_b32_e32 v130, v131, v130
	v_cvt_f32_u32_e32 v130, v130
	v_fmamk_f32 v131, v132, 0x30000000, v1
	v_rsq_f32_e32 v158, v131
	v_sub_u32_e32 v131, 32, v133
	v_ldexp_f32 v132, v130, v131
	v_ffbh_u32_e32 v130, v161
	v_min_u32_e32 v133, 32, v130
	v_lshlrev_b64 v[130:131], v133, v[160:161]
	v_min_u32_e32 v130, 1, v130
	v_or_b32_e32 v130, v131, v130
	v_cvt_f32_u32_e32 v130, v130
	v_fmamk_f32 v131, v132, 0x30000000, v1
	v_rsq_f32_e32 v160, v131
	v_sub_u32_e32 v131, 32, v133
	v_ldexp_f32 v132, v130, v131
	v_ffbh_u32_e32 v130, v163
	v_min_u32_e32 v133, 32, v130
	v_lshlrev_b64 v[130:131], v133, v[162:163]
	v_min_u32_e32 v130, 1, v130
	v_or_b32_e32 v130, v131, v130
	v_cvt_f32_u32_e32 v130, v130
	v_fmamk_f32 v131, v132, 0x30000000, v1
	v_rsq_f32_e32 v164, v131
	v_sub_u32_e32 v131, 32, v133
	v_ldexp_f32 v130, v130, v131
	v_fmamk_f32 v130, v130, 0x30000000, v1
	s_add_i32 s5, s5, s4
	v_rsq_f32_e32 v162, v130
	v_lshl_add_u32 v130, v151, 2, s5
	v_add_u32_e32 v248, 0x20000, v130
	ds_read2_b64 v[130:133], v248 offset1:16
	ds_read2_b64 v[134:137], v248 offset0:32 offset1:48
	ds_read2_b64 v[236:239], v248 offset0:64 offset1:80
	ds_read2_b64 v[240:243], v248 offset0:96 offset1:112
	v_pk_mul_f32 v[210:211], v[122:123], v[152:153] op_sel_hi:[1,0]
	v_pk_mul_f32 v[204:205], v[110:111], v[152:153] op_sel_hi:[1,0]
	v_pk_mul_f32 v[192:193], v[126:127], v[150:151] op_sel_hi:[1,0]
	v_pk_mul_f32 v[184:185], v[118:119], v[150:151] op_sel_hi:[1,0]
	v_pk_mul_f32 v[218:219], v[114:115], v[154:155] op_sel_hi:[1,0]
	v_pk_mul_f32 v[222:223], v[102:103], v[154:155] op_sel_hi:[1,0]
	v_pk_mul_f32 v[230:231], v[106:107], v[156:157] op_sel_hi:[1,0]
	v_pk_mul_f32 v[228:229], v[98:99], v[156:157] op_sel_hi:[1,0]
	v_pk_mul_f32 v[234:235], v[94:95], v[158:159] op_sel_hi:[1,0]
	v_pk_mul_f32 v[232:233], v[86:87], v[158:159] op_sel_hi:[1,0]
	v_pk_mul_f32 v[174:175], v[90:91], v[160:161] op_sel_hi:[1,0]
	v_pk_mul_f32 v[176:177], v[78:79], v[160:161] op_sel_hi:[1,0]
	v_pk_mul_f32 v[114:115], v[82:83], v[164:165] op_sel_hi:[1,0]
	v_pk_mul_f32 v[70:71], v[70:71], v[164:165] op_sel_hi:[1,0]
	v_pk_mul_f32 v[224:225], v[74:75], v[162:163] op_sel_hi:[1,0]
	v_pk_mul_f32 v[220:221], v[66:67], v[162:163] op_sel_hi:[1,0]
	s_waitcnt lgkmcnt(0)
	v_pk_fma_f32 v[74:75], v[210:211], v[236:237], v[240:241]
	v_pk_fma_f32 v[78:79], v[204:205], v[238:239], v[242:243]
	v_cmp_eq_u32_e64 s[6:7], 0, v153
	v_cmp_ne_u32_e64 s[4:5], 0, v153
	v_mov_b32_dpp v170, v224 row_shr:1 row_mask:0xf bank_mask:0xf bound_ctrl:1
	v_mov_b32_dpp v171, v225 row_shr:1 row_mask:0xf bank_mask:0xf bound_ctrl:1
	v_mov_b32_dpp v186, v114 row_shr:1 row_mask:0xf bank_mask:0xf bound_ctrl:1
	v_mov_b32_dpp v187, v115 row_shr:1 row_mask:0xf bank_mask:0xf bound_ctrl:1
	v_mov_b32_dpp v126, v220 row_shr:1 row_mask:0xf bank_mask:0xf bound_ctrl:1
	v_mov_b32_dpp v127, v221 row_shr:1 row_mask:0xf bank_mask:0xf bound_ctrl:1
	v_mov_b32_dpp v188, v70 row_shr:1 row_mask:0xf bank_mask:0xf bound_ctrl:1
	v_mov_b32_dpp v189, v71 row_shr:1 row_mask:0xf bank_mask:0xf bound_ctrl:1
	s_and_b64 vcc, exec, s[0:1]
	v_pk_fma_f32 v[166:167], v[192:193], v[236:237], v[240:241]
	v_pk_fma_f32 v[66:67], v[184:185], v[238:239], v[242:243]
	v_pk_fma_f32 v[180:181], v[218:219], v[236:237], v[240:241]
	v_pk_fma_f32 v[172:173], v[222:223], v[238:239], v[242:243]
	v_pk_fma_f32 v[190:191], v[236:237], v[230:231], v[240:241]
	v_pk_fma_f32 v[182:183], v[228:229], v[238:239], v[242:243]
	v_pk_fma_f32 v[208:209], v[236:237], v[234:235], v[240:241]
	v_pk_fma_f32 v[206:207], v[232:233], v[238:239], v[242:243]
	v_pk_fma_f32 v[216:217], v[236:237], v[174:175], v[240:241]
	v_pk_fma_f32 v[212:213], v[176:177], v[238:239], v[242:243]
	v_pk_fma_f32 v[226:227], v[236:237], v[114:115], v[240:241]
	v_pk_fma_f32 v[214:215], v[70:71], v[238:239], v[242:243]
	v_pk_fma_f32 v[122:123], v[236:237], v[224:225], v[240:241]
	v_pk_fma_f32 v[118:119], v[238:239], v[220:221], v[242:243]
	v_pk_fma_f32 v[178:179], v[192:193], v[134:135], v[74:75]
	v_pk_fma_f32 v[168:169], v[184:185], v[136:137], v[78:79]
	s_cbranch_vccnz .LBB0_983
	v_pk_fma_f32 v[74:75], v[134:135], v[170:171], v[166:167]
	s_mov_b32 s10, 0xbfb8aa3b
	v_pk_fma_f32 v[74:75], v[130:131], v[186:187], v[74:75]
	v_pk_fma_f32 v[78:79], v[136:137], v[126:127], v[66:67]
	v_pk_mul_f32 v[82:83], v[74:75], s[10:11] op_sel_hi:[1,0]
	v_pk_fma_f32 v[78:79], v[132:133], v[188:189], v[78:79]
	v_exp_f32_e32 v82, v82
	v_exp_f32_e32 v83, v83
	s_nop 0
	v_pk_add_f32 v[82:83], v[82:83], 1.0 op_sel_hi:[1,0]
	s_nop 0
	v_rcp_f32_e32 v82, v82
	v_rcp_f32_e32 v83, v83
	s_nop 0
	v_pk_mul_f32 v[74:75], v[74:75], v[82:83]
	s_nop 0
	v_pk_mul_f32 v[86:87], v[78:79], v[74:75]
	v_pk_fma_f32 v[74:75], v[130:131], v[170:171], v[178:179]
	v_pk_fma_f32 v[78:79], v[132:133], v[126:127], v[168:169]
	v_pk_mul_f32 v[82:83], v[74:75], s[10:11] op_sel_hi:[1,0]
	s_nop 0
	v_exp_f32_e32 v82, v82
	v_exp_f32_e32 v83, v83
	s_nop 0
	v_pk_add_f32 v[82:83], v[82:83], 1.0 op_sel_hi:[1,0]
	s_nop 0
	v_rcp_f32_e32 v82, v82
	v_rcp_f32_e32 v83, v83
	s_nop 0
	v_pk_mul_f32 v[74:75], v[74:75], v[82:83]
	s_nop 0
	v_pk_mul_f32 v[98:99], v[78:79], v[74:75]
	v_pk_fma_f32 v[74:75], v[210:211], v[134:135], v[180:181]
	v_pk_fma_f32 v[78:79], v[204:205], v[136:137], v[172:173]
	v_pk_fma_f32 v[74:75], v[192:193], v[130:131], v[74:75]
	v_pk_fma_f32 v[78:79], v[184:185], v[132:133], v[78:79]
	v_pk_mul_f32 v[82:83], v[74:75], s[10:11] op_sel_hi:[1,0]
	s_nop 0
	v_exp_f32_e32 v82, v82
	v_exp_f32_e32 v83, v83
	s_nop 0
	v_pk_add_f32 v[82:83], v[82:83], 1.0 op_sel_hi:[1,0]
	s_nop 0
	v_rcp_f32_e32 v82, v82
	v_rcp_f32_e32 v83, v83
	s_nop 0
	v_pk_mul_f32 v[74:75], v[74:75], v[82:83]
	s_nop 0
	v_pk_mul_f32 v[78:79], v[78:79], v[74:75]
	v_pk_fma_f32 v[74:75], v[134:135], v[218:219], v[190:191]
	v_pk_fma_f32 v[82:83], v[222:223], v[136:137], v[182:183]
	v_pk_fma_f32 v[74:75], v[130:131], v[210:211], v[74:75]
	v_pk_fma_f32 v[82:83], v[204:205], v[132:133], v[82:83]
	v_pk_mul_f32 v[90:91], v[74:75], s[10:11] op_sel_hi:[1,0]
	s_nop 0
	v_exp_f32_e32 v90, v90
	v_exp_f32_e32 v91, v91
	s_nop 0
	v_pk_add_f32 v[90:91], v[90:91], 1.0 op_sel_hi:[1,0]
	s_nop 0
	v_rcp_f32_e32 v90, v90
	v_rcp_f32_e32 v91, v91
	s_nop 0
	v_pk_mul_f32 v[74:75], v[74:75], v[90:91]
	s_nop 0
	v_pk_mul_f32 v[82:83], v[82:83], v[74:75]
	v_pk_fma_f32 v[74:75], v[134:135], v[230:231], v[208:209]
	v_pk_fma_f32 v[90:91], v[228:229], v[136:137], v[206:207]
	v_pk_fma_f32 v[74:75], v[130:131], v[218:219], v[74:75]
	v_pk_fma_f32 v[90:91], v[222:223], v[132:133], v[90:91]
	v_pk_mul_f32 v[94:95], v[74:75], s[10:11] op_sel_hi:[1,0]
	s_nop 0
	v_exp_f32_e32 v94, v94
	v_exp_f32_e32 v95, v95
	s_nop 0
	v_pk_add_f32 v[94:95], v[94:95], 1.0 op_sel_hi:[1,0]
	s_nop 0
	v_rcp_f32_e32 v94, v94
	v_rcp_f32_e32 v95, v95
	s_nop 0
	v_pk_mul_f32 v[74:75], v[74:75], v[94:95]
	s_nop 0
	v_pk_mul_f32 v[90:91], v[90:91], v[74:75]
	v_pk_fma_f32 v[74:75], v[134:135], v[234:235], v[216:217]
	v_pk_fma_f32 v[94:95], v[232:233], v[136:137], v[212:213]
	v_pk_fma_f32 v[74:75], v[130:131], v[230:231], v[74:75]
	v_pk_fma_f32 v[94:95], v[228:229], v[132:133], v[94:95]
	v_pk_mul_f32 v[102:103], v[74:75], s[10:11] op_sel_hi:[1,0]
	s_nop 0
	v_exp_f32_e32 v102, v102
	v_exp_f32_e32 v103, v103
	s_nop 0
	v_pk_add_f32 v[102:103], v[102:103], 1.0 op_sel_hi:[1,0]
	s_nop 0
	v_rcp_f32_e32 v102, v102
	v_rcp_f32_e32 v103, v103
	s_nop 0
	v_pk_mul_f32 v[74:75], v[74:75], v[102:103]
	s_nop 0
	v_pk_mul_f32 v[94:95], v[94:95], v[74:75]
	v_pk_fma_f32 v[74:75], v[134:135], v[174:175], v[226:227]
	v_pk_fma_f32 v[102:103], v[176:177], v[136:137], v[214:215]
	v_pk_fma_f32 v[74:75], v[130:131], v[234:235], v[74:75]
	v_pk_fma_f32 v[102:103], v[232:233], v[132:133], v[102:103]
	v_pk_mul_f32 v[106:107], v[74:75], s[10:11] op_sel_hi:[1,0]
	s_mov_b64 s[10:11], 0
	v_exp_f32_e32 v106, v106
	v_exp_f32_e32 v107, v107
	s_nop 0
	v_pk_add_f32 v[106:107], v[106:107], 1.0 op_sel_hi:[1,0]
	s_nop 0
	v_rcp_f32_e32 v106, v106
	v_rcp_f32_e32 v107, v107
	s_nop 0
	v_pk_mul_f32 v[74:75], v[74:75], v[106:107]
	s_nop 0
	v_pk_mul_f32 v[102:103], v[102:103], v[74:75]
	v_pk_fma_f32 v[74:75], v[134:135], v[114:115], v[122:123]
	s_nop 0
	v_pk_fma_f32 v[106:107], v[130:131], v[174:175], v[74:75]
	v_pk_fma_f32 v[74:75], v[136:137], v[70:71], v[118:119]
	s_nop 0
	v_pk_fma_f32 v[110:111], v[132:133], v[176:177], v[74:75]

.LBB0_1444:
	v_lshl_or_b32 v66, s44, 8, v199
	v_lshl_add_u32 v214, s45, 8, v197
	v_ashrrev_i32_e32 v67, 31, v66
	v_lshlrev_b64 v[216:217], 1, v[66:67]
	v_ashrrev_i32_e32 v215, 31, v214
	v_lshl_add_u64 v[66:67], s[86:87], 0, v[216:217]
	v_lshlrev_b64 v[200:201], 12, v[214:215]
	v_lshl_add_u64 v[68:69], v[66:67], 0, v[200:201]
	global_load_dwordx4 v[190:193], v[68:69], off
	global_load_dwordx4 v[178:181], v[68:69], off offset:256
	v_or_b32_e32 v68, 16, v214
	v_ashrrev_i32_e32 v69, 31, v68
	v_lshlrev_b64 v[230:231], 12, v[68:69]
	v_lshl_add_u64 v[68:69], v[66:67], 0, v[230:231]
	global_load_dwordx4 v[174:177], v[68:69], off
	global_load_dwordx4 v[170:173], v[68:69], off offset:256
	v_or_b32_e32 v68, 32, v214
	v_ashrrev_i32_e32 v69, 31, v68
	v_lshlrev_b64 v[228:229], 12, v[68:69]
	v_lshl_add_u64 v[68:69], v[66:67], 0, v[228:229]
	global_load_dwordx4 v[162:165], v[68:69], off
	global_load_dwordx4 v[158:161], v[68:69], off offset:256
	v_or_b32_e32 v68, 48, v214
	v_ashrrev_i32_e32 v69, 31, v68
	v_lshlrev_b64 v[226:227], 12, v[68:69]
	s_mov_b64 s[18:19], 0x80000
	v_lshl_add_u64 v[68:69], v[66:67], 0, v[226:227]
	v_lshl_add_u64 v[224:225], v[200:201], 0, s[18:19]
	s_mov_b64 s[18:19], 0x90000
	global_load_dwordx4 v[154:157], v[68:69], off
	global_load_dwordx4 v[150:153], v[68:69], off offset:256
	v_lshl_add_u64 v[222:223], v[200:201], 0, s[18:19]
	s_mov_b64 s[18:19], 0xa0000
	v_lshl_add_u64 v[220:221], v[200:201], 0, s[18:19]
	s_mov_b64 s[18:19], 0xb0000
	v_lshl_add_u64 v[218:219], v[200:201], 0, s[18:19]
	v_lshl_add_u64 v[200:201], s[86:87], 0, v[200:201]
	v_lshl_add_u64 v[232:233], v[200:201], 0, v[216:217]
	v_lshl_add_u64 v[68:69], v[66:67], 0, v[224:225]
	global_load_dwordx4 v[142:145], v[68:69], off
	global_load_dwordx4 v[130:133], v[68:69], off offset:256
	v_lshl_add_u64 v[68:69], v[66:67], 0, v[222:223]
	global_load_dwordx4 v[118:121], v[68:69], off
	global_load_dwordx4 v[106:109], v[68:69], off offset:256
	v_lshl_add_u64 v[68:69], v[66:67], 0, v[220:221]
	v_lshl_add_u64 v[66:67], v[66:67], 0, v[218:219]
	global_load_dwordx4 v[98:101], v[68:69], off
	global_load_dwordx4 v[86:89], v[68:69], off offset:256
	global_load_dwordx4 v[78:81], v[66:67], off
	s_nop 0
	global_load_dwordx4 v[66:69], v[66:67], off offset:256
	s_and_b64 vcc, exec, s[14:15]
	s_cbranch_vccz .Lalign_l8
	s_barrier
.Lalign_l8:
	s_movk_i32 s18, 0x80
	s_waitcnt vmcnt(0)
	v_lshlrev_b32_e32 v200, 16, v190
	v_and_b32_e32 v201, 0xffff0000, v190
	v_lshlrev_b32_e32 v190, 16, v191
	v_and_b32_e32 v191, 0xffff0000, v191
	v_pk_add_f32 v[186:187], v[186:187], v[200:201]
	v_pk_add_f32 v[188:189], v[188:189], v[190:191]
	v_cvt_pk_bf16_f32 v186, v186, v187
	v_cvt_pk_bf16_f32 v187, v188, v189
	v_lshlrev_b32_e32 v188, 16, v192
	v_and_b32_e32 v189, 0xffff0000, v192
	v_pk_add_f32 v[182:183], v[182:183], v[188:189]
	s_nop 0
	v_cvt_pk_bf16_f32 v188, v182, v183
	v_lshlrev_b32_e32 v182, 16, v193
	v_and_b32_e32 v183, 0xffff0000, v193
	v_pk_add_f32 v[182:183], v[184:185], v[182:183]
	v_and_b32_e32 v185, 0xffff0000, v187
	v_cvt_pk_bf16_f32 v189, v182, v183
	v_and_b32_e32 v183, 0xffff0000, v186
	v_lshlrev_b32_e32 v182, 16, v186
	v_mul_f32_e32 v183, v183, v183
	v_lshlrev_b32_e32 v184, 16, v187
	v_fmac_f32_e32 v183, v182, v182
	v_mul_f32_e32 v182, v185, v185
	global_store_dwordx4 v[232:233], v[186:189], off
	v_fmac_f32_e32 v182, v184, v184
	v_add_f32_e32 v182, v183, v182
	v_lshlrev_b32_e32 v186, 16, v188
	v_and_b32_e32 v187, 0xffff0000, v188
	v_lshlrev_b32_e32 v188, 16, v189
	v_and_b32_e32 v189, 0xffff0000, v189
	v_mul_f32_e32 v183, v187, v187
	v_mul_f32_e32 v184, v189, v189
	v_fmac_f32_e32 v183, v186, v186
	v_fmac_f32_e32 v184, v188, v188
	v_add_f32_e32 v183, v183, v184
	v_add_f32_e32 v184, v182, v183
	v_lshlrev_b32_e32 v182, 16, v178
	v_and_b32_e32 v183, 0xffff0000, v178
	v_lshlrev_b32_e32 v178, 16, v179
	v_and_b32_e32 v179, 0xffff0000, v179
	v_pk_add_f32 v[166:167], v[166:167], v[182:183]
	v_pk_add_f32 v[168:169], v[168:169], v[178:179]
	v_cvt_pk_bf16_f32 v166, v166, v167
	v_cvt_pk_bf16_f32 v167, v168, v169
	v_lshlrev_b32_e32 v168, 16, v180
	v_and_b32_e32 v169, 0xffff0000, v180
	v_pk_add_f32 v[146:147], v[146:147], v[168:169]
	s_nop 0
	v_cvt_pk_bf16_f32 v168, v146, v147
	v_lshlrev_b32_e32 v146, 16, v181
	v_and_b32_e32 v147, 0xffff0000, v181
	v_pk_add_f32 v[146:147], v[148:149], v[146:147]
	v_and_b32_e32 v149, 0xffff0000, v167
	v_cvt_pk_bf16_f32 v169, v146, v147
	v_and_b32_e32 v147, 0xffff0000, v166
	v_lshlrev_b32_e32 v146, 16, v166
	v_mul_f32_e32 v147, v147, v147
	v_lshlrev_b32_e32 v148, 16, v167
	v_fmac_f32_e32 v147, v146, v146
	v_mul_f32_e32 v146, v149, v149
	global_store_dwordx4 v[232:233], v[166:169], off offset:256
	v_fmac_f32_e32 v146, v148, v148
	v_add_f32_e32 v146, v147, v146
	v_and_b32_e32 v167, 0xffff0000, v168
	v_lshlrev_b32_e32 v166, 16, v168
	v_mul_f32_e32 v147, v167, v167
	v_fmac_f32_e32 v147, v166, v166
	v_lshlrev_b32_e32 v166, 16, v174
	v_and_b32_e32 v167, 0xffff0000, v174
	v_pk_add_f32 v[138:139], v[138:139], v[166:167]
	v_lshlrev_b32_e32 v166, 16, v175
	v_and_b32_e32 v167, 0xffff0000, v175
	v_pk_add_f32 v[140:141], v[140:141], v[166:167]
	v_cvt_pk_bf16_f32 v138, v138, v139
	v_cvt_pk_bf16_f32 v139, v140, v141
	v_lshlrev_b32_e32 v140, 16, v176
	v_and_b32_e32 v141, 0xffff0000, v176
	v_pk_add_f32 v[134:135], v[134:135], v[140:141]
	v_lshlrev_b32_e32 v168, 16, v169
	v_and_b32_e32 v169, 0xffff0000, v169
	v_cvt_pk_bf16_f32 v140, v134, v135
	v_lshlrev_b32_e32 v134, 16, v177
	v_and_b32_e32 v135, 0xffff0000, v177
	v_mul_f32_e32 v148, v169, v169
	v_pk_add_f32 v[134:135], v[136:137], v[134:135]
	v_fmac_f32_e32 v148, v168, v168
	v_cvt_pk_bf16_f32 v141, v134, v135
	v_and_b32_e32 v135, 0xffff0000, v138
	v_add_f32_e32 v147, v147, v148
	v_lshl_add_u64 v[148:149], s[86:87], 0, v[230:231]
	v_lshlrev_b32_e32 v134, 16, v138
	v_and_b32_e32 v137, 0xffff0000, v139
	v_mul_f32_e32 v135, v135, v135
	v_lshl_add_u64 v[148:149], v[148:149], 0, v[216:217]
	v_lshlrev_b32_e32 v136, 16, v139
	v_fmac_f32_e32 v135, v134, v134
	v_mul_f32_e32 v134, v137, v137
	global_store_dwordx4 v[148:149], v[138:141], off
	v_fmac_f32_e32 v134, v136, v136
	v_add_f32_e32 v134, v135, v134
	v_lshlrev_b32_e32 v138, 16, v140
	v_and_b32_e32 v139, 0xffff0000, v140
	v_lshlrev_b32_e32 v140, 16, v141
	v_and_b32_e32 v141, 0xffff0000, v141
	v_mul_f32_e32 v135, v139, v139
	v_mul_f32_e32 v136, v141, v141
	v_fmac_f32_e32 v135, v138, v138
	v_fmac_f32_e32 v136, v140, v140
	v_add_f32_e32 v135, v135, v136
	v_add_f32_e32 v136, v134, v135
	v_lshlrev_b32_e32 v134, 16, v170
	v_and_b32_e32 v135, 0xffff0000, v170
	v_pk_add_f32 v[126:127], v[126:127], v[134:135]
	v_lshlrev_b32_e32 v134, 16, v171
	v_and_b32_e32 v135, 0xffff0000, v171
	v_pk_add_f32 v[128:129], v[128:129], v[134:135]
	v_cvt_pk_bf16_f32 v126, v126, v127
	v_cvt_pk_bf16_f32 v127, v128, v129
	v_lshlrev_b32_e32 v128, 16, v172
	v_and_b32_e32 v129, 0xffff0000, v172
	v_pk_add_f32 v[122:123], v[122:123], v[128:129]
	v_add_f32_e32 v146, v146, v147
	v_cvt_pk_bf16_f32 v128, v122, v123
	v_lshlrev_b32_e32 v122, 16, v173
	v_and_b32_e32 v123, 0xffff0000, v173
	v_pk_add_f32 v[122:123], v[124:125], v[122:123]
	v_and_b32_e32 v125, 0xffff0000, v127
	v_cvt_pk_bf16_f32 v129, v122, v123
	v_and_b32_e32 v123, 0xffff0000, v126
	v_lshlrev_b32_e32 v122, 16, v126
	v_mul_f32_e32 v123, v123, v123
	v_lshlrev_b32_e32 v124, 16, v127
	v_fmac_f32_e32 v123, v122, v122
	v_mul_f32_e32 v122, v125, v125
	global_store_dwordx4 v[148:149], v[126:129], off offset:256
	v_fmac_f32_e32 v122, v124, v124
	v_add_f32_e32 v122, v123, v122
	v_and_b32_e32 v127, 0xffff0000, v128
	v_lshlrev_b32_e32 v126, 16, v128
	v_mul_f32_e32 v123, v127, v127
	v_fmac_f32_e32 v123, v126, v126
	v_lshlrev_b32_e32 v126, 16, v162
	v_and_b32_e32 v127, 0xffff0000, v162
	v_pk_add_f32 v[114:115], v[114:115], v[126:127]
	v_lshlrev_b32_e32 v126, 16, v163
	v_and_b32_e32 v127, 0xffff0000, v163
	v_pk_add_f32 v[116:117], v[116:117], v[126:127]
	v_cvt_pk_bf16_f32 v114, v114, v115
	v_cvt_pk_bf16_f32 v115, v116, v117
	v_lshlrev_b32_e32 v116, 16, v164
	v_and_b32_e32 v117, 0xffff0000, v164
	v_pk_add_f32 v[110:111], v[110:111], v[116:117]
	v_lshlrev_b32_e32 v128, 16, v129
	v_and_b32_e32 v129, 0xffff0000, v129
	v_cvt_pk_bf16_f32 v116, v110, v111
	v_lshlrev_b32_e32 v110, 16, v165
	v_and_b32_e32 v111, 0xffff0000, v165
	v_mul_f32_e32 v124, v129, v129
	v_pk_add_f32 v[110:111], v[112:113], v[110:111]
	v_fmac_f32_e32 v124, v128, v128
	v_cvt_pk_bf16_f32 v117, v110, v111
	v_and_b32_e32 v111, 0xffff0000, v114
	v_add_f32_e32 v123, v123, v124
	v_lshl_add_u64 v[124:125], s[86:87], 0, v[228:229]
	v_lshlrev_b32_e32 v110, 16, v114
	v_and_b32_e32 v113, 0xffff0000, v115
	v_mul_f32_e32 v111, v111, v111
	v_lshl_add_u64 v[124:125], v[124:125], 0, v[216:217]
	v_lshlrev_b32_e32 v112, 16, v115
	v_fmac_f32_e32 v111, v110, v110
	v_mul_f32_e32 v110, v113, v113
	global_store_dwordx4 v[124:125], v[114:117], off
	v_fmac_f32_e32 v110, v112, v112
	v_add_f32_e32 v110, v111, v110
	v_lshlrev_b32_e32 v114, 16, v116
	v_and_b32_e32 v115, 0xffff0000, v116
	v_lshlrev_b32_e32 v116, 16, v117
	v_and_b32_e32 v117, 0xffff0000, v117
	v_mul_f32_e32 v111, v115, v115
	v_mul_f32_e32 v112, v117, v117
	v_fmac_f32_e32 v111, v114, v114
	v_fmac_f32_e32 v112, v116, v116
	v_add_f32_e32 v111, v111, v112
	v_add_f32_e32 v112, v110, v111
	v_lshlrev_b32_e32 v110, 16, v158
	v_and_b32_e32 v111, 0xffff0000, v158
	v_pk_add_f32 v[102:103], v[102:103], v[110:111]
	v_lshlrev_b32_e32 v110, 16, v159
	v_and_b32_e32 v111, 0xffff0000, v159
	v_pk_add_f32 v[104:105], v[104:105], v[110:111]
	v_cvt_pk_bf16_f32 v102, v102, v103
	v_cvt_pk_bf16_f32 v103, v104, v105
	v_lshlrev_b32_e32 v104, 16, v160
	v_and_b32_e32 v105, 0xffff0000, v160
	v_pk_add_f32 v[94:95], v[94:95], v[104:105]
	v_add_f32_e32 v122, v122, v123
	v_cvt_pk_bf16_f32 v104, v94, v95
	v_lshlrev_b32_e32 v94, 16, v161
	v_and_b32_e32 v95, 0xffff0000, v161
	v_pk_add_f32 v[94:95], v[96:97], v[94:95]
	v_and_b32_e32 v97, 0xffff0000, v103
	v_cvt_pk_bf16_f32 v105, v94, v95
	v_and_b32_e32 v95, 0xffff0000, v102
	v_lshlrev_b32_e32 v94, 16, v102
	v_mul_f32_e32 v95, v95, v95
	v_lshlrev_b32_e32 v96, 16, v103
	v_fmac_f32_e32 v95, v94, v94
	v_mul_f32_e32 v94, v97, v97
	global_store_dwordx4 v[124:125], v[102:105], off offset:256
	v_fmac_f32_e32 v94, v96, v96
	v_add_f32_e32 v94, v95, v94
	v_and_b32_e32 v103, 0xffff0000, v104
	v_lshlrev_b32_e32 v102, 16, v104
	v_mul_f32_e32 v95, v103, v103
	v_fmac_f32_e32 v95, v102, v102
	v_lshlrev_b32_e32 v102, 16, v154
	v_and_b32_e32 v103, 0xffff0000, v154
	v_pk_add_f32 v[90:91], v[90:91], v[102:103]
	v_lshlrev_b32_e32 v102, 16, v155
	v_and_b32_e32 v103, 0xffff0000, v155
	v_pk_add_f32 v[92:93], v[92:93], v[102:103]
	v_cvt_pk_bf16_f32 v90, v90, v91
	v_cvt_pk_bf16_f32 v91, v92, v93
	v_lshlrev_b32_e32 v92, 16, v156
	v_and_b32_e32 v93, 0xffff0000, v156
	v_pk_add_f32 v[82:83], v[82:83], v[92:93]
	v_lshlrev_b32_e32 v104, 16, v105
	v_and_b32_e32 v105, 0xffff0000, v105
	v_cvt_pk_bf16_f32 v92, v82, v83
	v_lshlrev_b32_e32 v82, 16, v157
	v_and_b32_e32 v83, 0xffff0000, v157
	v_mul_f32_e32 v96, v105, v105
	v_pk_add_f32 v[82:83], v[84:85], v[82:83]
	v_fmac_f32_e32 v96, v104, v104
	v_cvt_pk_bf16_f32 v93, v82, v83
	v_and_b32_e32 v83, 0xffff0000, v90
	v_add_f32_e32 v95, v95, v96
	v_lshl_add_u64 v[96:97], s[86:87], 0, v[226:227]
	v_lshlrev_b32_e32 v82, 16, v90
	v_and_b32_e32 v85, 0xffff0000, v91
	v_mul_f32_e32 v83, v83, v83
	v_lshl_add_u64 v[96:97], v[96:97], 0, v[216:217]
	v_lshlrev_b32_e32 v84, 16, v91
	v_fmac_f32_e32 v83, v82, v82
	v_mul_f32_e32 v82, v85, v85
	global_store_dwordx4 v[96:97], v[90:93], off
	v_fmac_f32_e32 v82, v84, v84
	v_add_f32_e32 v82, v83, v82
	v_lshlrev_b32_e32 v90, 16, v92
	v_and_b32_e32 v91, 0xffff0000, v92
	v_lshlrev_b32_e32 v92, 16, v93
	v_and_b32_e32 v93, 0xffff0000, v93
	v_mul_f32_e32 v83, v91, v91
	v_mul_f32_e32 v84, v93, v93
	v_fmac_f32_e32 v83, v90, v90
	v_fmac_f32_e32 v84, v92, v92
	v_add_f32_e32 v83, v83, v84
	v_add_f32_e32 v84, v82, v83
	v_lshlrev_b32_e32 v82, 16, v150
	v_and_b32_e32 v83, 0xffff0000, v150
	v_pk_add_f32 v[74:75], v[74:75], v[82:83]
	v_lshlrev_b32_e32 v82, 16, v151
	v_and_b32_e32 v83, 0xffff0000, v151
	v_pk_add_f32 v[76:77], v[76:77], v[82:83]
	v_cvt_pk_bf16_f32 v74, v74, v75
	v_cvt_pk_bf16_f32 v75, v76, v77
	v_lshlrev_b32_e32 v76, 16, v152
	v_and_b32_e32 v77, 0xffff0000, v152
	v_pk_add_f32 v[70:71], v[70:71], v[76:77]
	v_add_f32_e32 v94, v94, v95
	v_cvt_pk_bf16_f32 v76, v70, v71
	v_lshlrev_b32_e32 v70, 16, v153
	v_and_b32_e32 v71, 0xffff0000, v153
	v_pk_add_f32 v[70:71], v[72:73], v[70:71]
	v_and_b32_e32 v73, 0xffff0000, v75
	v_cvt_pk_bf16_f32 v77, v70, v71
	v_and_b32_e32 v71, 0xffff0000, v74
	v_lshlrev_b32_e32 v70, 16, v74
	v_mul_f32_e32 v71, v71, v71
	v_lshlrev_b32_e32 v72, 16, v75
	v_fmac_f32_e32 v71, v70, v70
	v_mul_f32_e32 v70, v73, v73
	global_store_dwordx4 v[96:97], v[74:77], off offset:256
	v_fmac_f32_e32 v70, v72, v72
	v_add_f32_e32 v70, v71, v70
	v_lshlrev_b32_e32 v74, 16, v76
	v_and_b32_e32 v75, 0xffff0000, v76
	v_lshlrev_b32_e32 v76, 16, v77
	v_and_b32_e32 v77, 0xffff0000, v77
	v_mul_f32_e32 v71, v75, v75
	v_mul_f32_e32 v72, v77, v77
	v_fmac_f32_e32 v71, v74, v74
	v_fmac_f32_e32 v72, v76, v76
	v_add_f32_e32 v71, v71, v72
	v_lshlrev_b32_e32 v72, 16, v142
	v_and_b32_e32 v73, 0xffff0000, v142
	v_pk_add_f32 v[62:63], v[62:63], v[72:73]
	v_lshlrev_b32_e32 v72, 16, v143
	v_and_b32_e32 v73, 0xffff0000, v143
	v_pk_add_f32 v[64:65], v[64:65], v[72:73]
	v_cvt_pk_bf16_f32 v62, v62, v63
	v_cvt_pk_bf16_f32 v63, v64, v65
	v_lshlrev_b32_e32 v64, 16, v144
	v_and_b32_e32 v65, 0xffff0000, v144
	v_pk_add_f32 v[58:59], v[58:59], v[64:65]
	v_add_f32_e32 v70, v70, v71
	v_cvt_pk_bf16_f32 v64, v58, v59
	v_lshlrev_b32_e32 v58, 16, v145
	v_and_b32_e32 v59, 0xffff0000, v145
	v_pk_add_f32 v[58:59], v[60:61], v[58:59]
	v_add_f32_e32 v74, v84, v70
	v_cvt_pk_bf16_f32 v65, v58, v59
	v_and_b32_e32 v59, 0xffff0000, v62
	v_lshl_add_u64 v[70:71], s[86:87], 0, v[224:225]
	v_lshlrev_b32_e32 v58, 16, v62
	v_and_b32_e32 v61, 0xffff0000, v63
	v_mul_f32_e32 v59, v59, v59
	v_lshl_add_u64 v[70:71], v[70:71], 0, v[216:217]
	v_lshlrev_b32_e32 v60, 16, v63
	v_fmac_f32_e32 v59, v58, v58
	v_mul_f32_e32 v58, v61, v61
	global_store_dwordx4 v[70:71], v[62:65], off
	v_fmac_f32_e32 v58, v60, v60
	v_add_f32_e32 v58, v59, v58
	v_lshlrev_b32_e32 v62, 16, v64
	v_and_b32_e32 v63, 0xffff0000, v64
	v_lshlrev_b32_e32 v64, 16, v65
	v_and_b32_e32 v65, 0xffff0000, v65
	v_mul_f32_e32 v59, v63, v63
	v_mul_f32_e32 v60, v65, v65
	v_fmac_f32_e32 v59, v62, v62
	v_fmac_f32_e32 v60, v64, v64
	v_add_f32_e32 v59, v59, v60
	v_add_f32_e32 v60, v58, v59
	v_lshlrev_b32_e32 v58, 16, v130
	v_and_b32_e32 v59, 0xffff0000, v130
	v_pk_add_f32 v[54:55], v[54:55], v[58:59]
	v_lshlrev_b32_e32 v58, 16, v131
	v_and_b32_e32 v59, 0xffff0000, v131
	v_pk_add_f32 v[56:57], v[56:57], v[58:59]
	v_cvt_pk_bf16_f32 v54, v54, v55
	v_cvt_pk_bf16_f32 v55, v56, v57
	v_lshlrev_b32_e32 v56, 16, v132
	v_and_b32_e32 v57, 0xffff0000, v132
	v_pk_add_f32 v[50:51], v[50:51], v[56:57]
	v_add_f32_e32 v146, v184, v146
	v_cvt_pk_bf16_f32 v56, v50, v51
	v_lshlrev_b32_e32 v50, 16, v133
	v_and_b32_e32 v51, 0xffff0000, v133
	v_pk_add_f32 v[50:51], v[52:53], v[50:51]
	v_and_b32_e32 v53, 0xffff0000, v55
	v_cvt_pk_bf16_f32 v57, v50, v51
	v_and_b32_e32 v51, 0xffff0000, v54
	v_lshlrev_b32_e32 v50, 16, v54
	v_mul_f32_e32 v51, v51, v51
	v_lshlrev_b32_e32 v52, 16, v55
	v_fmac_f32_e32 v51, v50, v50
	v_mul_f32_e32 v50, v53, v53
	global_store_dwordx4 v[70:71], v[54:57], off offset:256
	v_fmac_f32_e32 v50, v52, v52
	v_add_f32_e32 v50, v51, v50
	v_lshlrev_b32_e32 v54, 16, v56
	v_and_b32_e32 v55, 0xffff0000, v56
	v_lshlrev_b32_e32 v56, 16, v57
	v_and_b32_e32 v57, 0xffff0000, v57
	v_mul_f32_e32 v51, v55, v55
	v_mul_f32_e32 v52, v57, v57
	v_fmac_f32_e32 v51, v54, v54
	v_fmac_f32_e32 v52, v56, v56
	v_add_f32_e32 v51, v51, v52
	v_lshlrev_b32_e32 v52, 16, v118
	v_and_b32_e32 v53, 0xffff0000, v118
	v_pk_add_f32 v[46:47], v[46:47], v[52:53]
	v_lshlrev_b32_e32 v52, 16, v119
	v_and_b32_e32 v53, 0xffff0000, v119
	v_pk_add_f32 v[48:49], v[48:49], v[52:53]
	v_cvt_pk_bf16_f32 v46, v46, v47
	v_cvt_pk_bf16_f32 v47, v48, v49
	v_lshlrev_b32_e32 v48, 16, v120
	v_and_b32_e32 v49, 0xffff0000, v120
	v_pk_add_f32 v[42:43], v[42:43], v[48:49]
	v_add_f32_e32 v50, v50, v51
	v_cvt_pk_bf16_f32 v48, v42, v43
	v_lshlrev_b32_e32 v42, 16, v121
	v_and_b32_e32 v43, 0xffff0000, v121
	v_pk_add_f32 v[42:43], v[44:45], v[42:43]
	v_add_f32_e32 v54, v60, v50
	v_cvt_pk_bf16_f32 v49, v42, v43
	v_and_b32_e32 v43, 0xffff0000, v46
	v_lshl_add_u64 v[50:51], s[86:87], 0, v[222:223]
	v_lshlrev_b32_e32 v42, 16, v46
	v_and_b32_e32 v45, 0xffff0000, v47
	v_mul_f32_e32 v43, v43, v43
	v_lshl_add_u64 v[50:51], v[50:51], 0, v[216:217]
	v_lshlrev_b32_e32 v44, 16, v47
	v_fmac_f32_e32 v43, v42, v42
	v_mul_f32_e32 v42, v45, v45
	global_store_dwordx4 v[50:51], v[46:49], off
	v_fmac_f32_e32 v42, v44, v44
	v_add_f32_e32 v42, v43, v42
	v_lshlrev_b32_e32 v46, 16, v48
	v_and_b32_e32 v47, 0xffff0000, v48
	v_lshlrev_b32_e32 v48, 16, v49
	v_and_b32_e32 v49, 0xffff0000, v49
	v_mul_f32_e32 v43, v47, v47
	v_mul_f32_e32 v44, v49, v49
	v_fmac_f32_e32 v43, v46, v46
	v_fmac_f32_e32 v44, v48, v48
	v_add_f32_e32 v43, v43, v44
	v_add_f32_e32 v44, v42, v43
	v_lshlrev_b32_e32 v42, 16, v106
	v_and_b32_e32 v43, 0xffff0000, v106
	v_pk_add_f32 v[38:39], v[38:39], v[42:43]
	v_lshlrev_b32_e32 v42, 16, v107
	v_and_b32_e32 v43, 0xffff0000, v107
	v_pk_add_f32 v[40:41], v[40:41], v[42:43]
	v_cvt_pk_bf16_f32 v38, v38, v39
	v_cvt_pk_bf16_f32 v39, v40, v41
	v_lshlrev_b32_e32 v40, 16, v108
	v_and_b32_e32 v41, 0xffff0000, v108
	v_pk_add_f32 v[34:35], v[34:35], v[40:41]
	v_add_f32_e32 v122, v136, v122
	v_cvt_pk_bf16_f32 v40, v34, v35
	v_lshlrev_b32_e32 v34, 16, v109
	v_and_b32_e32 v35, 0xffff0000, v109
	v_pk_add_f32 v[34:35], v[36:37], v[34:35]
	v_and_b32_e32 v37, 0xffff0000, v39
	v_cvt_pk_bf16_f32 v41, v34, v35
	v_and_b32_e32 v35, 0xffff0000, v38
	v_lshlrev_b32_e32 v34, 16, v38
	v_mul_f32_e32 v35, v35, v35
	v_lshlrev_b32_e32 v36, 16, v39
	v_fmac_f32_e32 v35, v34, v34
	v_mul_f32_e32 v34, v37, v37
	global_store_dwordx4 v[50:51], v[38:41], off offset:256
	v_fmac_f32_e32 v34, v36, v36
	v_add_f32_e32 v34, v35, v34
	v_lshlrev_b32_e32 v38, 16, v40
	v_and_b32_e32 v39, 0xffff0000, v40
	v_lshlrev_b32_e32 v40, 16, v41
	v_and_b32_e32 v41, 0xffff0000, v41
	v_mul_f32_e32 v35, v39, v39
	v_mul_f32_e32 v36, v41, v41
	v_fmac_f32_e32 v35, v38, v38
	v_fmac_f32_e32 v36, v40, v40
	v_add_f32_e32 v35, v35, v36
	v_lshlrev_b32_e32 v36, 16, v98
	v_and_b32_e32 v37, 0xffff0000, v98
	v_pk_add_f32 v[30:31], v[30:31], v[36:37]
	v_lshlrev_b32_e32 v36, 16, v99
	v_and_b32_e32 v37, 0xffff0000, v99
	v_pk_add_f32 v[32:33], v[32:33], v[36:37]
	v_cvt_pk_bf16_f32 v30, v30, v31
	v_cvt_pk_bf16_f32 v31, v32, v33
	v_lshlrev_b32_e32 v32, 16, v100
	v_and_b32_e32 v33, 0xffff0000, v100
	v_pk_add_f32 v[26:27], v[26:27], v[32:33]
	v_add_f32_e32 v34, v34, v35
	v_cvt_pk_bf16_f32 v32, v26, v27
	v_lshlrev_b32_e32 v26, 16, v101
	v_and_b32_e32 v27, 0xffff0000, v101
	v_pk_add_f32 v[26:27], v[28:29], v[26:27]
	v_add_f32_e32 v38, v44, v34
	v_cvt_pk_bf16_f32 v33, v26, v27
	v_and_b32_e32 v27, 0xffff0000, v30
	v_lshl_add_u64 v[34:35], s[86:87], 0, v[220:221]
	v_lshlrev_b32_e32 v26, 16, v30
	v_and_b32_e32 v29, 0xffff0000, v31
	v_mul_f32_e32 v27, v27, v27
	v_lshl_add_u64 v[34:35], v[34:35], 0, v[216:217]
	v_lshlrev_b32_e32 v28, 16, v31
	v_fmac_f32_e32 v27, v26, v26
	v_mul_f32_e32 v26, v29, v29
	global_store_dwordx4 v[34:35], v[30:33], off
	v_fmac_f32_e32 v26, v28, v28
	v_add_f32_e32 v26, v27, v26
	v_lshlrev_b32_e32 v30, 16, v32
	v_and_b32_e32 v31, 0xffff0000, v32
	v_lshlrev_b32_e32 v32, 16, v33
	v_and_b32_e32 v33, 0xffff0000, v33
	v_mul_f32_e32 v27, v31, v31
	v_mul_f32_e32 v28, v33, v33
	v_fmac_f32_e32 v27, v30, v30
	v_fmac_f32_e32 v28, v32, v32
	v_add_f32_e32 v27, v27, v28
	v_add_f32_e32 v28, v26, v27
	v_lshlrev_b32_e32 v26, 16, v86
	v_and_b32_e32 v27, 0xffff0000, v86
	v_pk_add_f32 v[22:23], v[22:23], v[26:27]
	v_lshlrev_b32_e32 v26, 16, v87
	v_and_b32_e32 v27, 0xffff0000, v87
	v_pk_add_f32 v[24:25], v[24:25], v[26:27]
	v_cvt_pk_bf16_f32 v22, v22, v23
	v_cvt_pk_bf16_f32 v23, v24, v25
	v_lshlrev_b32_e32 v24, 16, v88
	v_and_b32_e32 v25, 0xffff0000, v88
	v_pk_add_f32 v[18:19], v[18:19], v[24:25]
	v_add_f32_e32 v94, v112, v94
	v_cvt_pk_bf16_f32 v24, v18, v19
	v_lshlrev_b32_e32 v18, 16, v89
	v_and_b32_e32 v19, 0xffff0000, v89
	v_pk_add_f32 v[18:19], v[20:21], v[18:19]
	v_and_b32_e32 v21, 0xffff0000, v23
	v_cvt_pk_bf16_f32 v25, v18, v19
	v_and_b32_e32 v19, 0xffff0000, v22
	v_lshlrev_b32_e32 v18, 16, v22
	v_mul_f32_e32 v19, v19, v19
	v_lshlrev_b32_e32 v20, 16, v23
	v_fmac_f32_e32 v19, v18, v18
	v_mul_f32_e32 v18, v21, v21
	global_store_dwordx4 v[34:35], v[22:25], off offset:256
	v_fmac_f32_e32 v18, v20, v20
	v_add_f32_e32 v18, v19, v18
	v_lshlrev_b32_e32 v22, 16, v24
	v_and_b32_e32 v23, 0xffff0000, v24
	v_lshlrev_b32_e32 v24, 16, v25
	v_and_b32_e32 v25, 0xffff0000, v25
	v_mul_f32_e32 v19, v23, v23
	v_mul_f32_e32 v20, v25, v25
	v_fmac_f32_e32 v19, v22, v22
	v_fmac_f32_e32 v20, v24, v24
	v_add_f32_e32 v19, v19, v20
	v_lshlrev_b32_e32 v20, 16, v78
	v_and_b32_e32 v21, 0xffff0000, v78
	v_pk_add_f32 v[14:15], v[14:15], v[20:21]
	v_lshlrev_b32_e32 v20, 16, v79
	v_and_b32_e32 v21, 0xffff0000, v79
	v_pk_add_f32 v[16:17], v[16:17], v[20:21]
	v_cvt_pk_bf16_f32 v14, v14, v15
	v_cvt_pk_bf16_f32 v15, v16, v17
	v_lshlrev_b32_e32 v16, 16, v80
	v_and_b32_e32 v17, 0xffff0000, v80
	v_pk_add_f32 v[10:11], v[10:11], v[16:17]
	v_add_f32_e32 v18, v18, v19
	v_cvt_pk_bf16_f32 v16, v10, v11
	v_lshlrev_b32_e32 v10, 16, v81
	v_and_b32_e32 v11, 0xffff0000, v81
	v_pk_add_f32 v[10:11], v[12:13], v[10:11]
	v_add_f32_e32 v22, v28, v18
	v_cvt_pk_bf16_f32 v17, v10, v11
	v_and_b32_e32 v11, 0xffff0000, v14
	v_lshl_add_u64 v[18:19], s[86:87], 0, v[218:219]
	v_lshlrev_b32_e32 v10, 16, v14
	v_and_b32_e32 v13, 0xffff0000, v15
	v_mul_f32_e32 v11, v11, v11
	v_lshl_add_u64 v[18:19], v[18:19], 0, v[216:217]
	v_lshlrev_b32_e32 v12, 16, v15
	v_fmac_f32_e32 v11, v10, v10
	v_mul_f32_e32 v10, v13, v13
	global_store_dwordx4 v[18:19], v[14:17], off
	v_fmac_f32_e32 v10, v12, v12
	v_add_f32_e32 v10, v11, v10
	v_lshlrev_b32_e32 v14, 16, v16
	v_and_b32_e32 v15, 0xffff0000, v16
	v_lshlrev_b32_e32 v16, 16, v17
	v_and_b32_e32 v17, 0xffff0000, v17
	v_mul_f32_e32 v11, v15, v15
	v_mul_f32_e32 v12, v17, v17
	v_fmac_f32_e32 v11, v14, v14
	v_fmac_f32_e32 v12, v16, v16
	v_add_f32_e32 v11, v11, v12
	v_add_f32_e32 v12, v10, v11
	v_lshlrev_b32_e32 v10, 16, v66
	v_and_b32_e32 v11, 0xffff0000, v66
	v_pk_add_f32 v[6:7], v[6:7], v[10:11]
	v_lshlrev_b32_e32 v10, 16, v67
	v_and_b32_e32 v11, 0xffff0000, v67
	v_pk_add_f32 v[8:9], v[8:9], v[10:11]
	v_cvt_pk_bf16_f32 v6, v6, v7
	v_cvt_pk_bf16_f32 v7, v8, v9
	v_lshlrev_b32_e32 v8, 16, v68
	v_and_b32_e32 v9, 0xffff0000, v68
	v_pk_add_f32 v[2:3], v[2:3], v[8:9]
	s_nop 0
	v_cvt_pk_bf16_f32 v8, v2, v3
	v_lshlrev_b32_e32 v2, 16, v69
	v_and_b32_e32 v3, 0xffff0000, v69
	v_pk_add_f32 v[2:3], v[4:5], v[2:3]
	v_and_b32_e32 v5, 0xffff0000, v7
	v_cvt_pk_bf16_f32 v9, v2, v3
	v_and_b32_e32 v3, 0xffff0000, v6
	v_lshlrev_b32_e32 v2, 16, v6
	v_mul_f32_e32 v3, v3, v3
	v_lshlrev_b32_e32 v4, 16, v7
	v_fmac_f32_e32 v3, v2, v2
	v_mul_f32_e32 v2, v5, v5
	global_store_dwordx4 v[18:19], v[6:9], off offset:256
	v_fmac_f32_e32 v2, v4, v4
	v_add_f32_e32 v2, v3, v2
	v_lshlrev_b32_e32 v6, 16, v8
	v_and_b32_e32 v7, 0xffff0000, v8
	v_lshlrev_b32_e32 v8, 16, v9
	v_and_b32_e32 v9, 0xffff0000, v9
	v_mul_f32_e32 v3, v7, v7
	v_mul_f32_e32 v4, v9, v9
	v_fmac_f32_e32 v3, v6, v6
	v_fmac_f32_e32 v4, v8, v8
	v_add_f32_e32 v3, v3, v4
	v_add_f32_e32 v2, v2, v3
	v_add_f32_e32 v8, v12, v2
	v_mov_b32_e32 v2, v0
	s_nop 0
	v_lshlrev_b32_e32 v10, 2, v2
	v_bitop3_b32 v2, v10, 64, v196 bitop3:0x6c
	ds_bpermute_b32 v3, v2, v146
	ds_bpermute_b32 v4, v2, v122
	ds_bpermute_b32 v5, v2, v94
	ds_bpermute_b32 v6, v2, v74
	ds_bpermute_b32 v7, v2, v54
	ds_bpermute_b32 v9, v2, v38
	ds_bpermute_b32 v11, v2, v22
	ds_bpermute_b32 v12, v2, v8
	s_waitcnt lgkmcnt(7)
	v_add_f32_e32 v2, v146, v3
	s_waitcnt lgkmcnt(6)
	v_add_f32_e32 v3, v122, v4
	s_waitcnt lgkmcnt(5)
	v_add_f32_e32 v4, v94, v5
	s_waitcnt lgkmcnt(4)
	v_add_f32_e32 v5, v74, v6
	s_waitcnt lgkmcnt(3)
	v_add_f32_e32 v6, v54, v7
	s_waitcnt lgkmcnt(2)
	v_add_f32_e32 v7, v38, v9
	s_waitcnt lgkmcnt(1)
	v_add_f32_e32 v9, v22, v11
	s_waitcnt lgkmcnt(0)
	v_add_f32_e32 v11, v8, v12
	v_bitop3_b32 v17, v10, s18, v196 bitop3:0x6c
	ds_bpermute_b32 v8, v17, v2
	ds_bpermute_b32 v10, v17, v3
	ds_bpermute_b32 v12, v17, v4
	ds_bpermute_b32 v13, v17, v5
	ds_bpermute_b32 v14, v17, v6
	ds_bpermute_b32 v15, v17, v7
	ds_bpermute_b32 v16, v17, v9
	ds_bpermute_b32 v17, v17, v11
	s_and_saveexec_b64 s[18:19], s[2:3]
	s_cbranch_execz .LBB0_1446
	s_waitcnt lgkmcnt(5)
	v_add_f32_e32 v12, v4, v12
	v_add_f32_e32 v4, v2, v8
	s_mov_b32 s20, 0x49800000
	v_fma_f32 v4, v4, s20, 0.5
	v_trunc_f32_e32 v4, v4
	s_waitcnt lgkmcnt(4)
	v_add_f32_e32 v13, v5, v13
	v_mul_f32_e32 v5, 0x2f800000, v4
	v_floor_f32_e32 v5, v5
	v_fmac_f32_e32 v4, 0xcf800000, v5
	v_cvt_u32_f32_e32 v4, v4
	v_cvt_u32_f32_e32 v5, v5
	v_add_f32_e32 v10, v3, v10
	v_lshl_add_u64 v[2:3], v[214:215], 3, s[10:11]
	s_waitcnt lgkmcnt(3)
	v_add_f32_e32 v6, v6, v14
	global_atomic_add_x2 v[2:3], v[4:5], off
	v_fma_f32 v4, v10, s20, 0.5
	v_trunc_f32_e32 v4, v4
	v_mul_f32_e32 v5, 0x2f800000, v4
	v_floor_f32_e32 v5, v5
	v_fmac_f32_e32 v4, 0xcf800000, v5
	v_cvt_u32_f32_e32 v4, v4
	v_cvt_u32_f32_e32 v5, v5
	s_waitcnt lgkmcnt(2)
	v_add_f32_e32 v7, v7, v15
	s_waitcnt lgkmcnt(1)
	v_add_f32_e32 v9, v9, v16
	s_waitcnt lgkmcnt(0)
	v_add_f32_e32 v11, v11, v17
	global_atomic_add_x2 v[2:3], v[4:5], off offset:128
	v_fma_f32 v4, v12, s20, 0.5
	v_trunc_f32_e32 v4, v4
	v_mul_f32_e32 v5, 0x2f800000, v4
	v_floor_f32_e32 v5, v5
	v_fmac_f32_e32 v4, 0xcf800000, v5
	v_cvt_u32_f32_e32 v4, v4
	v_cvt_u32_f32_e32 v5, v5
	global_atomic_add_x2 v[2:3], v[4:5], off offset:256
	v_fma_f32 v4, v13, s20, 0.5
	v_trunc_f32_e32 v4, v4
	v_mul_f32_e32 v5, 0x2f800000, v4
	v_floor_f32_e32 v5, v5
	v_fmac_f32_e32 v4, 0xcf800000, v5
	v_cvt_u32_f32_e32 v4, v4
	v_cvt_u32_f32_e32 v5, v5
	global_atomic_add_x2 v[2:3], v[4:5], off offset:384
	v_fma_f32 v4, v6, s20, 0.5
	v_trunc_f32_e32 v4, v4
	v_mul_f32_e32 v5, 0x2f800000, v4
	v_floor_f32_e32 v5, v5
	v_fmac_f32_e32 v4, 0xcf800000, v5
	v_cvt_u32_f32_e32 v4, v4
	v_cvt_u32_f32_e32 v5, v5
	global_atomic_add_x2 v[2:3], v[4:5], off offset:1024
	v_fma_f32 v4, v7, s20, 0.5
	v_trunc_f32_e32 v4, v4
	v_mul_f32_e32 v5, 0x2f800000, v4
	v_floor_f32_e32 v5, v5
	v_fmac_f32_e32 v4, 0xcf800000, v5
	v_cvt_u32_f32_e32 v4, v4
	v_cvt_u32_f32_e32 v5, v5
	global_atomic_add_x2 v[2:3], v[4:5], off offset:1152
	v_fma_f32 v4, v9, s20, 0.5
	v_trunc_f32_e32 v4, v4
	v_mul_f32_e32 v5, 0x2f800000, v4
	v_floor_f32_e32 v5, v5
	v_fmac_f32_e32 v4, 0xcf800000, v5
	v_cvt_u32_f32_e32 v4, v4
	v_cvt_u32_f32_e32 v5, v5
	global_atomic_add_x2 v[2:3], v[4:5], off offset:1280
	v_fma_f32 v4, v11, s20, 0.5
	v_trunc_f32_e32 v4, v4
	v_mul_f32_e32 v5, 0x2f800000, v4
	v_floor_f32_e32 v5, v5
	v_fmac_f32_e32 v4, 0xcf800000, v5
	v_cvt_u32_f32_e32 v4, v4
	v_cvt_u32_f32_e32 v5, v5
	global_atomic_add_x2 v[2:3], v[4:5], off offset:1408
